# first K-loop iteration peeled with C=0 on each accumulator's first MFMA in phases 1/6/7/8; accumulator zero-init removed there
# speedup vs baseline: 1.0036x; 1.0036x over previous
; #define PG8_STAGE(bufoff, gbase, voff) do { _Pragma("unroll") for (int _i = 0; _i < 2; ++_i) \
;         __builtin_amdgcn_global_load_lds((const unsigned*)((const char*)(gbase) + (voff)[_i]), (LAS unsigned*)(lds + (bufoff) + ldsw + _i * 8192), 16, 0, 0); } while (0)
; #define PG8_LDA(dst, b, h) do { _Pragma("unroll") for (int m = 0; m < 4; ++m) _Pragma("unroll") for (int k = 0; k < 2; ++k) dst[m][k] = *(const LAS bf16x8*)(lds + PG8_SA(b, h) + aoff + m * 2048 + k * 1024); } while (0)
; #define PG8_LDB(dst, b, h) do { _Pragma("unroll") for (int n = 0; n < 2; ++n) _Pragma("unroll") for (int k = 0; k < 2; ++k) dst[n][k] = *(const LAS bf16x8*)(lds + PG8_SB(b, h) + boff + n * 2048 + k * 1024); } while (0)
; #define PG8_MMA(ai, bj, At, Bt) do { __builtin_amdgcn_s_setprio(1); _Pragma("unroll") for (int m = 0; m < 4; ++m) _Pragma("unroll") for (int n = 0; n < 2; ++n) _Pragma("unroll") for (int k = 0; k < 2; ++k) \
;         acc[ai][bj][m][n] = __builtin_amdgcn_mfma_f32_16x16x32_bf16(Bt[n][k], At[m][k], acc[ai][bj][m][n], 0, 0, 0); __builtin_amdgcn_s_setprio(0); } while (0)
; #define PG8_WAIT_V(n) asm volatile("s_waitcnt vmcnt(" #n ")" ::: "memory")
; #define PG8_WAIT_L(n) asm volatile("s_waitcnt lgkmcnt(" #n ")" ::: "memory")
; template <class Epi, class Sched>
; __device__ __forceinline__ void gemm_phase(LAS unsigned char* lds, const int K, const Sched& S, const Epi& E) {
;     ...
;         for (int t = 0; t < nt; t += 2) {
;             const bool last = (t == nt - 2);
;             const char* a1 = cA + (size_t)(t + 1) * kstep;
;             const char* a2 = last ? nA : cA + (size_t)(t + 2) * kstep; const char* b2 = last ? nB : cB + (size_t)(t + 2) * kstep;
;             const char* a3 = a2 + kstep; const char* b3 = b2 + kstep;
;             PG8_LDB(B0, 0, 0); PG8_SCHED; PG8_LDA(At, 0, 0); PG8_STAGE(PG8_SA(1, 1), a1 + hstep, voffA);
;             PG8_WAIT_L(8); PG8_BAR; PG8_WAIT_L(0); PG8_MMA(0, 0, At, B0); PG8_BAR; PG8_SCHED;
;             PG8_LDB(B1, 0, 1); PG8_STAGE(PG8_SB(0, 0), b2, voffB);
;             PG8_BAR; PG8_WAIT_L(0); PG8_MMA(0, 1, At, B1); PG8_BAR;
;             PG8_LDA(At, 0, 1); PG8_STAGE(PG8_SA(0, 0), a2, voffA);
;             PG8_BAR; PG8_WAIT_L(0); PG8_MMA(1, 0, At, B0); PG8_BAR; PG8_SCHED;
;             PG8_STAGE(PG8_SB(0, 1), b2 + hstep, voffB);
;             PG8_WAIT_V(6); PG8_BAR; PG8_MMA(1, 1, At, B1); PG8_BAR;
.LBB0_254:
	s_ashr_i32 s53, s52, 31
	s_lshl_b64 s[54:55], s[52:53], 19
	s_add_u32 s54, s33, s54
	s_addc_u32 s55, s70, s55
	s_and_b64 s[56:57], s[66:67], exec
	s_cselect_b32 s12, s55, s63
	s_cselect_b32 s53, s54, s62
	s_ashr_i32 s51, s50, 31
	s_lshl_b64 s[56:57], s[50:51], 19
	s_add_u32 s56, s10, s56
	s_addc_u32 s57, s11, s57
	s_and_b64 s[66:67], s[66:67], exec
	s_cselect_b32 s51, s57, s65
	s_cselect_b32 s59, s56, s64
	s_add_u32 s62, s62, 0x40080
	s_addc_u32 s63, s63, 0
	s_add_u32 s61, s64, 0x100
	s_addc_u32 s93, s65, 0
	s_mov_b32 s94, -2
	s_waitcnt lgkmcnt(0)
	s_cmpk_eq_i32 s58, 0x10
	s_cselect_b32 s101, 1, 0
	s_cmpk_eq_i32 s60, 0x100
	s_cselect_b32 s100, 2, 0
	s_or_b32 s101, s101, s100
	v_readfirstlane_b32 s100, v230
	s_lshr_b32 s100, s100, 5
	s_and_b32 s100, s100, 4
	s_bitcmp1_b32 s101, 0
	s_cselect_b32 s100, s100, 0
	s_or_b32 s101, s101, s100
	ds_read_b128 v[146:149], v153
	ds_read_b128 v[160:163], v153 offset:1024
	ds_read_b128 v[164:167], v153 offset:2048
	ds_read_b128 v[168:171], v153 offset:3072
	s_add_u32 s64, s62, 0xfffc0080
	s_addc_u32 s65, s63, -1
	s_cmp_eq_u32 s94, 12
	s_cselect_b32 s67, s12, s65
	s_cselect_b32 s66, s53, s64
	s_cselect_b32 s65, s51, s93
	s_cselect_b32 s64, s59, s61
	v_lshl_add_u64 v[150:151], s[62:63], 0, v[142:143]
	s_add_i32 m0, s5, 0xc000
	ds_read_b128 v[172:175], v154
	ds_read_b128 v[176:179], v154 offset:1024
	ds_read_b128 v[180:183], v154 offset:2048
	ds_read_b128 v[184:187], v154 offset:3072
	ds_read_b128 v[188:191], v154 offset:4096
	ds_read_b128 v[192:195], v154 offset:5120
	ds_read_b128 v[196:199], v154 offset:6144
	ds_read_b128 v[200:203], v154 offset:7168
	global_load_lds_dwordx4 v[150:151], off
	v_lshl_add_u64 v[150:151], s[62:63], 0, v[144:145]
	s_add_i32 m0, s5, 0xe000
	s_nop 0
	global_load_lds_dwordx4 v[150:151], off
	s_waitcnt lgkmcnt(8)
	s_barrier
	s_waitcnt lgkmcnt(0)
	s_bitcmp1_b32 s101, 2
	s_cbranch_scc1 .Lskp1_0_p
	s_setprio 1
	s_waitcnt lgkmcnt(0)
	v_mfma_f32_16x16x32_bf16 v[124:127], v[146:149], v[172:175], 0
	v_mfma_f32_16x16x32_bf16 v[120:123], v[164:167], v[172:175], 0
	v_mfma_f32_16x16x32_bf16 v[108:111], v[146:149], v[180:183], 0
	v_mfma_f32_16x16x32_bf16 v[104:107], v[164:167], v[180:183], 0
	v_mfma_f32_16x16x32_bf16 v[92:95], v[146:149], v[188:191], 0
	v_mfma_f32_16x16x32_bf16 v[88:91], v[164:167], v[188:191], 0
	v_mfma_f32_16x16x32_bf16 v[76:79], v[146:149], v[196:199], 0
	v_mfma_f32_16x16x32_bf16 v[72:75], v[164:167], v[196:199], 0
	v_mfma_f32_16x16x32_bf16 v[124:127], v[160:163], v[176:179], v[124:127]
	v_mfma_f32_16x16x32_bf16 v[120:123], v[168:171], v[176:179], v[120:123]
	v_mfma_f32_16x16x32_bf16 v[108:111], v[160:163], v[184:187], v[108:111]
	v_mfma_f32_16x16x32_bf16 v[104:107], v[168:171], v[184:187], v[104:107]
	v_mfma_f32_16x16x32_bf16 v[92:95], v[160:163], v[192:195], v[92:95]
	v_mfma_f32_16x16x32_bf16 v[88:91], v[168:171], v[192:195], v[88:91]
	v_mfma_f32_16x16x32_bf16 v[76:79], v[160:163], v[200:203], v[76:79]
	v_mfma_f32_16x16x32_bf16 v[72:75], v[168:171], v[200:203], v[72:75]
	s_setprio 0
.Lskp1_0_p:
	s_barrier
	s_add_i32 s95, s79, s4
	v_lshl_add_u64 v[150:151], s[64:65], 0, v[130:131]
	s_mov_b32 m0, s95
	ds_read_b128 v[204:207], v155
	ds_read_b128 v[208:211], v155 offset:1024
	ds_read_b128 v[212:215], v155 offset:2048
	ds_read_b128 v[216:219], v155 offset:3072
	global_load_lds_dwordx4 v[150:151], off
	v_lshl_add_u64 v[220:221], s[64:65], 0, v[134:135]
	s_add_i32 m0, s95, 0x2000
	s_nop 0
	global_load_lds_dwordx4 v[220:221], off
	s_barrier
	s_waitcnt lgkmcnt(0)
	s_bitcmp1_b32 s101, 0
	s_cbranch_scc1 .Lskp1_1_p
	s_setprio 1
	s_waitcnt lgkmcnt(0)
	v_mfma_f32_16x16x32_bf16 v[116:119], v[204:207], v[172:175], 0
	v_mfma_f32_16x16x32_bf16 v[112:115], v[212:215], v[172:175], 0
	v_mfma_f32_16x16x32_bf16 v[100:103], v[204:207], v[180:183], 0
	v_mfma_f32_16x16x32_bf16 v[96:99], v[212:215], v[180:183], 0
	v_mfma_f32_16x16x32_bf16 v[84:87], v[204:207], v[188:191], 0
	v_mfma_f32_16x16x32_bf16 v[80:83], v[212:215], v[188:191], 0
	v_mfma_f32_16x16x32_bf16 v[68:71], v[204:207], v[196:199], 0
	v_mfma_f32_16x16x32_bf16 v[64:67], v[212:215], v[196:199], 0
	v_mfma_f32_16x16x32_bf16 v[116:119], v[208:211], v[176:179], v[116:119]
	v_mfma_f32_16x16x32_bf16 v[112:115], v[216:219], v[176:179], v[112:115]
	v_mfma_f32_16x16x32_bf16 v[100:103], v[208:211], v[184:187], v[100:103]
	v_mfma_f32_16x16x32_bf16 v[96:99], v[216:219], v[184:187], v[96:99]
	v_mfma_f32_16x16x32_bf16 v[84:87], v[208:211], v[192:195], v[84:87]
	v_mfma_f32_16x16x32_bf16 v[80:83], v[216:219], v[192:195], v[80:83]
	v_mfma_f32_16x16x32_bf16 v[68:71], v[208:211], v[200:203], v[68:71]
	v_mfma_f32_16x16x32_bf16 v[64:67], v[216:219], v[200:203], v[64:67]
	s_setprio 0
; #define PG8_STAGE(bufoff, gbase, voff) do { _Pragma("unroll") for (int _i = 0; _i < 2; ++_i) \
;         __builtin_amdgcn_global_load_lds((const unsigned*)((const char*)(gbase) + (voff)[_i]), (LAS unsigned*)(lds + (bufoff) + ldsw + _i * 8192), 16, 0, 0); } while (0)
; #define PG8_LDA(dst, b, h) do { _Pragma("unroll") for (int m = 0; m < 4; ++m) _Pragma("unroll") for (int k = 0; k < 2; ++k) dst[m][k] = *(const LAS bf16x8*)(lds + PG8_SA(b, h) + aoff + m * 2048 + k * 1024); } while (0)
; #define PG8_MMA(ai, bj, At, Bt) do { __builtin_amdgcn_s_setprio(1); _Pragma("unroll") for (int m = 0; m < 4; ++m) _Pragma("unroll") for (int n = 0; n < 2; ++n) _Pragma("unroll") for (int k = 0; k < 2; ++k) \
;         acc[ai][bj][m][n] = __builtin_amdgcn_mfma_f32_16x16x32_bf16(Bt[n][k], At[m][k], acc[ai][bj][m][n], 0, 0, 0); __builtin_amdgcn_s_setprio(0); } while (0)
; #define PG8_WAIT_V(n) asm volatile("s_waitcnt vmcnt(" #n ")" ::: "memory")
; #define PG8_WAIT_L(n) asm volatile("s_waitcnt lgkmcnt(" #n ")" ::: "memory")
; #define PG8_BAR __builtin_amdgcn_s_barrier()
; #define PG8_SCHED __builtin_amdgcn_sched_barrier(0)
; template <class Epi, class Sched>
; __device__ __forceinline__ void gemm_phase(LAS unsigned char* lds, const int K, const Sched& S, const Epi& E) {
;     ...
;             PG8_LDA(At, 0, 1); PG8_STAGE(PG8_SA(0, 0), a2, voffA);
;             PG8_BAR; PG8_WAIT_L(0); PG8_MMA(1, 0, At, B0); PG8_BAR; PG8_SCHED;
;             PG8_STAGE(PG8_SB(0, 1), b2 + hstep, voffB);
;             PG8_WAIT_V(6); PG8_BAR; PG8_MMA(1, 1, At, B1); PG8_BAR;
.Lskp1_1_p:
	s_mov_b32 m0, s5
	v_lshl_add_u64 v[222:223], s[66:67], 0, v[128:129]
	s_barrier
	ds_read_b128 v[172:175], v154 offset:16384
	ds_read_b128 v[176:179], v154 offset:17408
	ds_read_b128 v[180:183], v154 offset:18432
	ds_read_b128 v[184:187], v154 offset:19456
	ds_read_b128 v[188:191], v154 offset:20480
	ds_read_b128 v[192:195], v154 offset:21504
	ds_read_b128 v[196:199], v154 offset:22528
	ds_read_b128 v[200:203], v154 offset:23552
	global_load_lds_dwordx4 v[222:223], off
	v_lshl_add_u64 v[224:225], s[66:67], 0, v[132:133]
	s_mov_b32 m0, s71
	s_nop 0
	global_load_lds_dwordx4 v[224:225], off
	s_barrier
	s_waitcnt lgkmcnt(0)
	s_and_b32 s100, s101, 6
	s_cbranch_scc1 .Lskp1_2_p
	s_setprio 1
	s_waitcnt lgkmcnt(0)
	v_mfma_f32_16x16x32_bf16 v[60:63], v[146:149], v[172:175], 0
	v_mfma_f32_16x16x32_bf16 v[56:59], v[164:167], v[172:175], 0
	v_mfma_f32_16x16x32_bf16 v[44:47], v[146:149], v[180:183], 0
	v_mfma_f32_16x16x32_bf16 v[40:43], v[164:167], v[180:183], 0
	v_mfma_f32_16x16x32_bf16 v[28:31], v[146:149], v[188:191], 0
	v_mfma_f32_16x16x32_bf16 v[24:27], v[164:167], v[188:191], 0
	v_mfma_f32_16x16x32_bf16 v[12:15], v[146:149], v[196:199], 0
	v_mfma_f32_16x16x32_bf16 v[8:11], v[164:167], v[196:199], 0
	v_mfma_f32_16x16x32_bf16 v[60:63], v[160:163], v[176:179], v[60:63]
	v_mfma_f32_16x16x32_bf16 v[56:59], v[168:171], v[176:179], v[56:59]
	v_mfma_f32_16x16x32_bf16 v[44:47], v[160:163], v[184:187], v[44:47]
	v_mfma_f32_16x16x32_bf16 v[40:43], v[168:171], v[184:187], v[40:43]
	v_mfma_f32_16x16x32_bf16 v[28:31], v[160:163], v[192:195], v[28:31]
	v_mfma_f32_16x16x32_bf16 v[24:27], v[168:171], v[192:195], v[24:27]
	v_mfma_f32_16x16x32_bf16 v[12:15], v[160:163], v[200:203], v[12:15]
	v_mfma_f32_16x16x32_bf16 v[8:11], v[168:171], v[200:203], v[8:11]
	s_setprio 0
.Lskp1_2_p:
	s_barrier
	s_add_u32 s96, s64, 0x40000
	s_addc_u32 s97, s65, 0
	s_add_i32 s95, s80, s4
	v_lshl_add_u64 v[146:147], s[96:97], 0, v[130:131]
	s_mov_b32 m0, s95
	s_nop 0
	global_load_lds_dwordx4 v[146:147], off
	v_lshl_add_u64 v[146:147], s[96:97], 0, v[134:135]
	s_add_i32 m0, s95, 0x2000
	s_nop 0
	global_load_lds_dwordx4 v[146:147], off
	s_waitcnt vmcnt(6)
	s_barrier
	s_and_b32 s100, s101, 3
	s_cbranch_scc1 .Lskp1_3_p
	s_setprio 1
	v_mfma_f32_16x16x32_bf16 v[52:55], v[204:207], v[172:175], 0
	v_mfma_f32_16x16x32_bf16 v[48:51], v[212:215], v[172:175], 0
	v_mfma_f32_16x16x32_bf16 v[36:39], v[204:207], v[180:183], 0
	v_mfma_f32_16x16x32_bf16 v[32:35], v[212:215], v[180:183], 0
	v_mfma_f32_16x16x32_bf16 v[20:23], v[204:207], v[188:191], 0
	v_mfma_f32_16x16x32_bf16 v[16:19], v[212:215], v[188:191], 0
	v_mfma_f32_16x16x32_bf16 v[4:7], v[204:207], v[196:199], 0
	v_mfma_f32_16x16x32_bf16 v[0:3], v[212:215], v[196:199], 0
	v_mfma_f32_16x16x32_bf16 v[52:55], v[208:211], v[176:179], v[52:55]
	v_mfma_f32_16x16x32_bf16 v[48:51], v[216:219], v[176:179], v[48:51]
	v_mfma_f32_16x16x32_bf16 v[36:39], v[208:211], v[184:187], v[36:39]
	v_mfma_f32_16x16x32_bf16 v[32:35], v[216:219], v[184:187], v[32:35]
	v_mfma_f32_16x16x32_bf16 v[20:23], v[208:211], v[192:195], v[20:23]
	v_mfma_f32_16x16x32_bf16 v[16:19], v[216:219], v[192:195], v[16:19]
	v_mfma_f32_16x16x32_bf16 v[4:7], v[208:211], v[200:203], v[4:7]
	v_mfma_f32_16x16x32_bf16 v[0:3], v[216:219], v[200:203], v[0:3]
	s_setprio 0

; #define PG8_STAGE(bufoff, gbase, voff) do { _Pragma("unroll") for (int _i = 0; _i < 2; ++_i) \
;         __builtin_amdgcn_global_load_lds((const unsigned*)((const char*)(gbase) + (voff)[_i]), (LAS unsigned*)(lds + (bufoff) + ldsw + _i * 8192), 16, 0, 0); } while (0)
; #define PG8_LDA(dst, b, h) do { _Pragma("unroll") for (int m = 0; m < 4; ++m) _Pragma("unroll") for (int k = 0; k < 2; ++k) dst[m][k] = *(const LAS bf16x8*)(lds + PG8_SA(b, h) + aoff + m * 2048 + k * 1024); } while (0)
; #define PG8_LDB(dst, b, h) do { _Pragma("unroll") for (int n = 0; n < 2; ++n) _Pragma("unroll") for (int k = 0; k < 2; ++k) dst[n][k] = *(const LAS bf16x8*)(lds + PG8_SB(b, h) + boff + n * 2048 + k * 1024); } while (0)
; #define PG8_MMA(ai, bj, At, Bt) do { __builtin_amdgcn_s_setprio(1); _Pragma("unroll") for (int m = 0; m < 4; ++m) _Pragma("unroll") for (int n = 0; n < 2; ++n) _Pragma("unroll") for (int k = 0; k < 2; ++k) \
;         acc[ai][bj][m][n] = __builtin_amdgcn_mfma_f32_16x16x32_bf16(Bt[n][k], At[m][k], acc[ai][bj][m][n], 0, 0, 0); __builtin_amdgcn_s_setprio(0); } while (0)
; #define PG8_WAIT_L(n) asm volatile("s_waitcnt lgkmcnt(" #n ")" ::: "memory")
; #define PG8_BAR __builtin_amdgcn_s_barrier()
; #define PG8_SCHED __builtin_amdgcn_sched_barrier(0)
; template <class Epi, class Sched>
; __device__ __forceinline__ void gemm_phase(LAS unsigned char* lds, const int K, const Sched& S, const Epi& E) {
;     ...
;         for (int t = 0; t < nt; t += 2) {
;             const bool last = (t == nt - 2);
;             const char* a1 = cA + (size_t)(t + 1) * kstep;
;             const char* a2 = last ? nA : cA + (size_t)(t + 2) * kstep; const char* b2 = last ? nB : cB + (size_t)(t + 2) * kstep;
;             const char* a3 = a2 + kstep; const char* b3 = b2 + kstep;
;             PG8_LDB(B0, 0, 0); PG8_SCHED; PG8_LDA(At, 0, 0); PG8_STAGE(PG8_SA(1, 1), a1 + hstep, voffA);
;             PG8_WAIT_L(8); PG8_BAR; PG8_WAIT_L(0); PG8_MMA(0, 0, At, B0); PG8_BAR; PG8_SCHED;
.Lskp1_7_p:
	s_add_i32 s94, s94, 2
	s_add_u32 s62, s62, 0x100
	s_addc_u32 s63, s63, 0
	s_add_u32 s61, s61, 0x100
	s_addc_u32 s93, s93, 0
	s_cmp_gt_u32 s94, 13
	s_barrier
	s_cbranch_scc0 .LBB0_255
.LBB0_255:
	ds_read_b128 v[146:149], v153
	ds_read_b128 v[160:163], v153 offset:1024
	ds_read_b128 v[164:167], v153 offset:2048
	ds_read_b128 v[168:171], v153 offset:3072
	s_add_u32 s64, s62, 0xfffc0080
	s_addc_u32 s65, s63, -1
	s_cmp_eq_u32 s94, 12
	s_cselect_b32 s67, s12, s65
	s_cselect_b32 s66, s53, s64
	s_cselect_b32 s65, s51, s93
	s_cselect_b32 s64, s59, s61
	v_lshl_add_u64 v[150:151], s[62:63], 0, v[142:143]
	s_add_i32 m0, s5, 0xc000
	ds_read_b128 v[172:175], v154
	ds_read_b128 v[176:179], v154 offset:1024
	ds_read_b128 v[180:183], v154 offset:2048
	ds_read_b128 v[184:187], v154 offset:3072
	ds_read_b128 v[188:191], v154 offset:4096
	ds_read_b128 v[192:195], v154 offset:5120
	ds_read_b128 v[196:199], v154 offset:6144
	ds_read_b128 v[200:203], v154 offset:7168
	global_load_lds_dwordx4 v[150:151], off
	v_lshl_add_u64 v[150:151], s[62:63], 0, v[144:145]
	s_add_i32 m0, s5, 0xe000
	s_nop 0
	global_load_lds_dwordx4 v[150:151], off
	s_waitcnt lgkmcnt(8)
	s_barrier
	s_waitcnt lgkmcnt(0)
	s_bitcmp1_b32 s101, 2
	s_cbranch_scc1 .Lskp1_0
	s_setprio 1
	s_waitcnt lgkmcnt(0)
	v_mfma_f32_16x16x32_bf16 v[124:127], v[146:149], v[172:175], v[124:127]
	v_mfma_f32_16x16x32_bf16 v[120:123], v[164:167], v[172:175], v[120:123]
	v_mfma_f32_16x16x32_bf16 v[108:111], v[146:149], v[180:183], v[108:111]
	v_mfma_f32_16x16x32_bf16 v[104:107], v[164:167], v[180:183], v[104:107]
	v_mfma_f32_16x16x32_bf16 v[92:95], v[146:149], v[188:191], v[92:95]
	v_mfma_f32_16x16x32_bf16 v[88:91], v[164:167], v[188:191], v[88:91]
	v_mfma_f32_16x16x32_bf16 v[76:79], v[146:149], v[196:199], v[76:79]
	v_mfma_f32_16x16x32_bf16 v[72:75], v[164:167], v[196:199], v[72:75]
	v_mfma_f32_16x16x32_bf16 v[124:127], v[160:163], v[176:179], v[124:127]
	v_mfma_f32_16x16x32_bf16 v[120:123], v[168:171], v[176:179], v[120:123]
	v_mfma_f32_16x16x32_bf16 v[108:111], v[160:163], v[184:187], v[108:111]
	v_mfma_f32_16x16x32_bf16 v[104:107], v[168:171], v[184:187], v[104:107]
	v_mfma_f32_16x16x32_bf16 v[92:95], v[160:163], v[192:195], v[92:95]
	v_mfma_f32_16x16x32_bf16 v[88:91], v[168:171], v[192:195], v[88:91]
	v_mfma_f32_16x16x32_bf16 v[76:79], v[160:163], v[200:203], v[76:79]
	v_mfma_f32_16x16x32_bf16 v[72:75], v[168:171], v[200:203], v[72:75]
	s_setprio 0

; #define PG8_STAGE(bufoff, gbase, voff) do { _Pragma("unroll") for (int _i = 0; _i < 2; ++_i) \
;         __builtin_amdgcn_global_load_lds((const unsigned*)((const char*)(gbase) + (voff)[_i]), (LAS unsigned*)(lds + (bufoff) + ldsw + _i * 8192), 16, 0, 0); } while (0)
; #define PG8_LDA(dst, b, h) do { _Pragma("unroll") for (int m = 0; m < 4; ++m) _Pragma("unroll") for (int k = 0; k < 2; ++k) dst[m][k] = *(const LAS bf16x8*)(lds + PG8_SA(b, h) + aoff + m * 2048 + k * 1024); } while (0)
; #define PG8_LDB(dst, b, h) do { _Pragma("unroll") for (int n = 0; n < 2; ++n) _Pragma("unroll") for (int k = 0; k < 2; ++k) dst[n][k] = *(const LAS bf16x8*)(lds + PG8_SB(b, h) + boff + n * 2048 + k * 1024); } while (0)
; #define PG8_MMA(ai, bj, At, Bt) do { __builtin_amdgcn_s_setprio(1); _Pragma("unroll") for (int m = 0; m < 4; ++m) _Pragma("unroll") for (int n = 0; n < 2; ++n) _Pragma("unroll") for (int k = 0; k < 2; ++k) \
;         acc[ai][bj][m][n] = __builtin_amdgcn_mfma_f32_16x16x32_bf16(Bt[n][k], At[m][k], acc[ai][bj][m][n], 0, 0, 0); __builtin_amdgcn_s_setprio(0); } while (0)
; #define PG8_WAIT_L(n) asm volatile("s_waitcnt lgkmcnt(" #n ")" ::: "memory")
; #define PG8_BAR __builtin_amdgcn_s_barrier()
; #define PG8_SCHED __builtin_amdgcn_sched_barrier(0)
; template <class Epi, class Sched>
; __device__ __forceinline__ void gemm_phase(LAS unsigned char* lds, const int K, const Sched& S, const Epi& E) {
;     ...
;             PG8_LDB(B0, 0, 0); PG8_SCHED; PG8_LDA(At, 0, 0); PG8_STAGE(PG8_SA(1, 1), a1 + hstep, voffA);
;             PG8_WAIT_L(8); PG8_BAR; PG8_WAIT_L(0); PG8_MMA(0, 0, At, B0); PG8_BAR; PG8_SCHED;
;             PG8_LDB(B1, 0, 1); PG8_STAGE(PG8_SB(0, 0), b2, voffB);
;             PG8_BAR; PG8_WAIT_L(0); PG8_MMA(0, 1, At, B1); PG8_BAR;
;             PG8_LDA(At, 0, 1); PG8_STAGE(PG8_SA(0, 0), a2, voffA);
;             PG8_BAR; PG8_WAIT_L(0); PG8_MMA(1, 0, At, B0); PG8_BAR; PG8_SCHED;
.LBB0_1279:
	s_ashr_i32 s35, s34, 31
	s_lshl_b64 s[36:37], s[34:35], 19
	s_add_u32 s36, s33, s36
	s_addc_u32 s37, s42, s37
	s_and_b64 s[38:39], s[14:15], exec
	s_cselect_b32 s11, s37, s41
	s_cselect_b32 s13, s36, s40
	s_ashr_i32 s31, s30, 31
	s_lshl_b64 s[38:39], s[30:31], 19
	s_add_u32 s38, s3, s38
	s_addc_u32 s39, s4, s39
	s_and_b64 s[14:15], s[14:15], exec
	s_cselect_b32 s31, s39, s17
	s_cselect_b32 s35, s38, s16
	s_add_u32 s14, s40, 0x40080
	s_addc_u32 s15, s41, 0
	s_add_u32 s56, s16, 0x100
	s_addc_u32 s57, s17, 0
	s_mov_b32 s58, -2
	s_waitcnt lgkmcnt(0)
	s_cmpk_eq_i32 s12, 0x100
	s_cselect_b64 vcc, -1, 0
	ds_read_b128 v[128:131], v223
	ds_read_b128 v[132:135], v223 offset:1024
	ds_read_b128 v[136:139], v223 offset:2048
	ds_read_b128 v[140:143], v223 offset:3072
	s_add_u32 s16, s14, 0xfffc0080
	s_addc_u32 s17, s15, -1
	s_cmp_eq_u32 s58, 12
	s_cselect_b32 s41, s11, s17
	s_cselect_b32 s40, s13, s16
	s_cselect_b32 s17, s31, s57
	s_cselect_b32 s16, s35, s56
	v_lshl_add_u64 v[176:177], s[14:15], 0, v[192:193]
	s_add_i32 m0, s5, 0xc000
	ds_read_b128 v[144:147], v224
	ds_read_b128 v[148:151], v224 offset:1024
	ds_read_b128 v[152:155], v224 offset:2048
	ds_read_b128 v[156:159], v224 offset:3072
	ds_read_b128 v[160:163], v224 offset:4096
	ds_read_b128 v[164:167], v224 offset:5120
	ds_read_b128 v[168:171], v224 offset:6144
	ds_read_b128 v[172:175], v224 offset:7168
	global_load_lds_dwordx4 v[176:177], off
	v_lshl_add_u64 v[176:177], s[14:15], 0, v[194:195]
	s_add_i32 m0, s5, 0xe000
	s_nop 0
	global_load_lds_dwordx4 v[176:177], off
	s_waitcnt lgkmcnt(8)
	s_barrier
	s_waitcnt lgkmcnt(0)
	s_setprio 1
	s_waitcnt lgkmcnt(0)
	v_mfma_f32_16x16x32_bf16 v[124:127], v[128:131], v[144:147], 0
	v_mfma_f32_16x16x32_bf16 v[120:123], v[136:139], v[144:147], 0
	v_mfma_f32_16x16x32_bf16 v[108:111], v[128:131], v[152:155], 0
	v_mfma_f32_16x16x32_bf16 v[104:107], v[136:139], v[152:155], 0
	v_mfma_f32_16x16x32_bf16 v[92:95], v[128:131], v[160:163], 0
	v_mfma_f32_16x16x32_bf16 v[88:91], v[136:139], v[160:163], 0
	v_mfma_f32_16x16x32_bf16 v[76:79], v[128:131], v[168:171], 0
	v_mfma_f32_16x16x32_bf16 v[72:75], v[136:139], v[168:171], 0
	v_mfma_f32_16x16x32_bf16 v[124:127], v[132:135], v[148:151], v[124:127]
	v_mfma_f32_16x16x32_bf16 v[120:123], v[140:143], v[148:151], v[120:123]
	v_mfma_f32_16x16x32_bf16 v[108:111], v[132:135], v[156:159], v[108:111]
	v_mfma_f32_16x16x32_bf16 v[104:107], v[140:143], v[156:159], v[104:107]
	v_mfma_f32_16x16x32_bf16 v[92:95], v[132:135], v[164:167], v[92:95]
	v_mfma_f32_16x16x32_bf16 v[88:91], v[140:143], v[164:167], v[88:91]
	v_mfma_f32_16x16x32_bf16 v[76:79], v[132:135], v[172:175], v[76:79]
	v_mfma_f32_16x16x32_bf16 v[72:75], v[140:143], v[172:175], v[72:75]
	s_setprio 0
	s_barrier
	s_add_i32 s59, s50, s1
	v_lshl_add_u64 v[204:205], s[16:17], 0, v[186:187]
	s_mov_b32 m0, s59
	ds_read_b128 v[176:179], v225
	ds_read_b128 v[180:183], v225 offset:1024
	ds_read_b128 v[196:199], v225 offset:2048
	ds_read_b128 v[200:203], v225 offset:3072
	global_load_lds_dwordx4 v[204:205], off
	v_lshl_add_u64 v[206:207], s[16:17], 0, v[190:191]
	s_add_i32 m0, s59, 0x2000
	s_nop 0
	global_load_lds_dwordx4 v[206:207], off
	s_barrier
	s_waitcnt lgkmcnt(0)
	s_setprio 1
	s_waitcnt lgkmcnt(0)
	v_mfma_f32_16x16x32_bf16 v[116:119], v[176:179], v[144:147], 0
	v_mfma_f32_16x16x32_bf16 v[112:115], v[196:199], v[144:147], 0
	v_mfma_f32_16x16x32_bf16 v[100:103], v[176:179], v[152:155], 0
	v_mfma_f32_16x16x32_bf16 v[96:99], v[196:199], v[152:155], 0
	v_mfma_f32_16x16x32_bf16 v[84:87], v[176:179], v[160:163], 0
	v_mfma_f32_16x16x32_bf16 v[80:83], v[196:199], v[160:163], 0
	v_mfma_f32_16x16x32_bf16 v[68:71], v[176:179], v[168:171], 0
	v_mfma_f32_16x16x32_bf16 v[64:67], v[196:199], v[168:171], 0
	v_mfma_f32_16x16x32_bf16 v[116:119], v[180:183], v[148:151], v[116:119]
	v_mfma_f32_16x16x32_bf16 v[112:115], v[200:203], v[148:151], v[112:115]
	v_mfma_f32_16x16x32_bf16 v[100:103], v[180:183], v[156:159], v[100:103]
	v_mfma_f32_16x16x32_bf16 v[96:99], v[200:203], v[156:159], v[96:99]
	v_mfma_f32_16x16x32_bf16 v[84:87], v[180:183], v[164:167], v[84:87]
	v_mfma_f32_16x16x32_bf16 v[80:83], v[200:203], v[164:167], v[80:83]
	v_mfma_f32_16x16x32_bf16 v[68:71], v[180:183], v[172:175], v[68:71]
	v_mfma_f32_16x16x32_bf16 v[64:67], v[200:203], v[172:175], v[64:67]
	s_setprio 0
	s_mov_b32 m0, s5
	v_lshl_add_u64 v[208:209], s[40:41], 0, v[184:185]
	s_barrier
	ds_read_b128 v[144:147], v224 offset:16384
	ds_read_b128 v[148:151], v224 offset:17408
	ds_read_b128 v[152:155], v224 offset:18432
	ds_read_b128 v[156:159], v224 offset:19456
	ds_read_b128 v[160:163], v224 offset:20480
	ds_read_b128 v[164:167], v224 offset:21504
	ds_read_b128 v[168:171], v224 offset:22528
	ds_read_b128 v[172:175], v224 offset:23552
	global_load_lds_dwordx4 v[208:209], off
	v_lshl_add_u64 v[210:211], s[40:41], 0, v[188:189]
	s_mov_b32 m0, s43
	s_nop 0
	global_load_lds_dwordx4 v[210:211], off
	s_barrier
	s_waitcnt lgkmcnt(0)
	s_cbranch_vccnz .Lskp6_2_p
	s_setprio 1
	s_waitcnt lgkmcnt(0)
	v_mfma_f32_16x16x32_bf16 v[60:63], v[128:131], v[144:147], 0
	v_mfma_f32_16x16x32_bf16 v[56:59], v[136:139], v[144:147], 0
	v_mfma_f32_16x16x32_bf16 v[44:47], v[128:131], v[152:155], 0
	v_mfma_f32_16x16x32_bf16 v[40:43], v[136:139], v[152:155], 0
	v_mfma_f32_16x16x32_bf16 v[28:31], v[128:131], v[160:163], 0
	v_mfma_f32_16x16x32_bf16 v[24:27], v[136:139], v[160:163], 0
	v_mfma_f32_16x16x32_bf16 v[12:15], v[128:131], v[168:171], 0
	v_mfma_f32_16x16x32_bf16 v[8:11], v[136:139], v[168:171], 0
	v_mfma_f32_16x16x32_bf16 v[60:63], v[132:135], v[148:151], v[60:63]
	v_mfma_f32_16x16x32_bf16 v[56:59], v[140:143], v[148:151], v[56:59]
	v_mfma_f32_16x16x32_bf16 v[44:47], v[132:135], v[156:159], v[44:47]
	v_mfma_f32_16x16x32_bf16 v[40:43], v[140:143], v[156:159], v[40:43]
	v_mfma_f32_16x16x32_bf16 v[28:31], v[132:135], v[164:167], v[28:31]
	v_mfma_f32_16x16x32_bf16 v[24:27], v[140:143], v[164:167], v[24:27]
	v_mfma_f32_16x16x32_bf16 v[12:15], v[132:135], v[172:175], v[12:15]
	v_mfma_f32_16x16x32_bf16 v[8:11], v[140:143], v[172:175], v[8:11]
	s_setprio 0
; #define PG8_STAGE(bufoff, gbase, voff) do { _Pragma("unroll") for (int _i = 0; _i < 2; ++_i) \
;         __builtin_amdgcn_global_load_lds((const unsigned*)((const char*)(gbase) + (voff)[_i]), (LAS unsigned*)(lds + (bufoff) + ldsw + _i * 8192), 16, 0, 0); } while (0)
; #define PG8_MMA(ai, bj, At, Bt) do { __builtin_amdgcn_s_setprio(1); _Pragma("unroll") for (int m = 0; m < 4; ++m) _Pragma("unroll") for (int n = 0; n < 2; ++n) _Pragma("unroll") for (int k = 0; k < 2; ++k) \
;         acc[ai][bj][m][n] = __builtin_amdgcn_mfma_f32_16x16x32_bf16(Bt[n][k], At[m][k], acc[ai][bj][m][n], 0, 0, 0); __builtin_amdgcn_s_setprio(0); } while (0)
; #define PG8_WAIT_V(n) asm volatile("s_waitcnt vmcnt(" #n ")" ::: "memory")
; #define PG8_BAR __builtin_amdgcn_s_barrier()
; template <class Epi, class Sched>
; __device__ __forceinline__ void gemm_phase(LAS unsigned char* lds, const int K, const Sched& S, const Epi& E) {
;     ...
;             PG8_STAGE(PG8_SB(0, 1), b2 + hstep, voffB);
;             PG8_WAIT_V(6); PG8_BAR; PG8_MMA(1, 1, At, B1); PG8_BAR;
.Lskp6_2_p:
	s_barrier
	s_add_u32 s60, s16, 0x40000
	s_addc_u32 s61, s17, 0
	s_add_i32 s59, s51, s1
	v_lshl_add_u64 v[128:129], s[60:61], 0, v[186:187]
	s_mov_b32 m0, s59
	s_nop 0
	global_load_lds_dwordx4 v[128:129], off
	v_lshl_add_u64 v[128:129], s[60:61], 0, v[190:191]
	s_add_i32 m0, s59, 0x2000
	s_nop 0
	global_load_lds_dwordx4 v[128:129], off
	s_waitcnt vmcnt(6)
	s_barrier
	s_cbranch_vccnz .Lskp6_3_p
	s_setprio 1
	v_mfma_f32_16x16x32_bf16 v[52:55], v[176:179], v[144:147], 0
	v_mfma_f32_16x16x32_bf16 v[48:51], v[196:199], v[144:147], 0
	v_mfma_f32_16x16x32_bf16 v[36:39], v[176:179], v[152:155], 0
	v_mfma_f32_16x16x32_bf16 v[32:35], v[196:199], v[152:155], 0
	v_mfma_f32_16x16x32_bf16 v[20:23], v[176:179], v[160:163], 0
	v_mfma_f32_16x16x32_bf16 v[16:19], v[196:199], v[160:163], 0
	v_mfma_f32_16x16x32_bf16 v[4:7], v[176:179], v[168:171], 0
	v_mfma_f32_16x16x32_bf16 v[0:3], v[196:199], v[168:171], 0
	v_mfma_f32_16x16x32_bf16 v[52:55], v[180:183], v[148:151], v[52:55]
	v_mfma_f32_16x16x32_bf16 v[48:51], v[200:203], v[148:151], v[48:51]
	v_mfma_f32_16x16x32_bf16 v[36:39], v[180:183], v[156:159], v[36:39]
	v_mfma_f32_16x16x32_bf16 v[32:35], v[200:203], v[156:159], v[32:35]
	v_mfma_f32_16x16x32_bf16 v[20:23], v[180:183], v[164:167], v[20:23]
	v_mfma_f32_16x16x32_bf16 v[16:19], v[200:203], v[164:167], v[16:19]
	v_mfma_f32_16x16x32_bf16 v[4:7], v[180:183], v[172:175], v[4:7]
	v_mfma_f32_16x16x32_bf16 v[0:3], v[200:203], v[172:175], v[0:3]
	s_setprio 0

; #define PG8_STAGE(bufoff, gbase, voff) do { _Pragma("unroll") for (int _i = 0; _i < 2; ++_i) \
;         __builtin_amdgcn_global_load_lds((const unsigned*)((const char*)(gbase) + (voff)[_i]), (LAS unsigned*)(lds + (bufoff) + ldsw + _i * 8192), 16, 0, 0); } while (0)
; #define PG8_LDA(dst, b, h) do { _Pragma("unroll") for (int m = 0; m < 4; ++m) _Pragma("unroll") for (int k = 0; k < 2; ++k) dst[m][k] = *(const LAS bf16x8*)(lds + PG8_SA(b, h) + aoff + m * 2048 + k * 1024); } while (0)
; #define PG8_LDB(dst, b, h) do { _Pragma("unroll") for (int n = 0; n < 2; ++n) _Pragma("unroll") for (int k = 0; k < 2; ++k) dst[n][k] = *(const LAS bf16x8*)(lds + PG8_SB(b, h) + boff + n * 2048 + k * 1024); } while (0)
; #define PG8_MMA(ai, bj, At, Bt) do { __builtin_amdgcn_s_setprio(1); _Pragma("unroll") for (int m = 0; m < 4; ++m) _Pragma("unroll") for (int n = 0; n < 2; ++n) _Pragma("unroll") for (int k = 0; k < 2; ++k) \
;         acc[ai][bj][m][n] = __builtin_amdgcn_mfma_f32_16x16x32_bf16(Bt[n][k], At[m][k], acc[ai][bj][m][n], 0, 0, 0); __builtin_amdgcn_s_setprio(0); } while (0)
; #define PG8_WAIT_L(n) asm volatile("s_waitcnt lgkmcnt(" #n ")" ::: "memory")
; #define PG8_BAR __builtin_amdgcn_s_barrier()
; #define PG8_SCHED __builtin_amdgcn_sched_barrier(0)
; template <class Epi, class Sched>
; __device__ __forceinline__ void gemm_phase(LAS unsigned char* lds, const int K, const Sched& S, const Epi& E) {
;     ...
;         for (int t = 0; t < nt; t += 2) {
;             const bool last = (t == nt - 2);
;             const char* a1 = cA + (size_t)(t + 1) * kstep;
;             const char* a2 = last ? nA : cA + (size_t)(t + 2) * kstep; const char* b2 = last ? nB : cB + (size_t)(t + 2) * kstep;
;             const char* a3 = a2 + kstep; const char* b3 = b2 + kstep;
;             PG8_LDB(B0, 0, 0); PG8_SCHED; PG8_LDA(At, 0, 0); PG8_STAGE(PG8_SA(1, 1), a1 + hstep, voffA);
;             PG8_WAIT_L(8); PG8_BAR; PG8_WAIT_L(0); PG8_MMA(0, 0, At, B0); PG8_BAR; PG8_SCHED;
;             PG8_LDB(B1, 0, 1); PG8_STAGE(PG8_SB(0, 0), b2, voffB);
;             PG8_BAR; PG8_WAIT_L(0); PG8_MMA(0, 1, At, B1); PG8_BAR;
;             PG8_LDA(At, 0, 1); PG8_STAGE(PG8_SA(0, 0), a2, voffA);
;             PG8_BAR; PG8_WAIT_L(0); PG8_MMA(1, 0, At, B0); PG8_BAR; PG8_SCHED;
.Lskp6_7_p:
	s_add_i32 s58, s58, 2
	s_add_u32 s14, s14, 0x100
	s_addc_u32 s15, s15, 0
	s_add_u32 s56, s56, 0x100
	s_addc_u32 s57, s57, 0
	s_cmp_gt_u32 s58, 13
	s_barrier
	s_cbranch_scc0 .LBB0_1280
.LBB0_1280:
	ds_read_b128 v[128:131], v223
	ds_read_b128 v[132:135], v223 offset:1024
	ds_read_b128 v[136:139], v223 offset:2048
	ds_read_b128 v[140:143], v223 offset:3072
	s_add_u32 s16, s14, 0xfffc0080
	s_addc_u32 s17, s15, -1
	s_cmp_eq_u32 s58, 12
	s_cselect_b32 s41, s11, s17
	s_cselect_b32 s40, s13, s16
	s_cselect_b32 s17, s31, s57
	s_cselect_b32 s16, s35, s56
	v_lshl_add_u64 v[176:177], s[14:15], 0, v[192:193]
	s_add_i32 m0, s5, 0xc000
	ds_read_b128 v[144:147], v224
	ds_read_b128 v[148:151], v224 offset:1024
	ds_read_b128 v[152:155], v224 offset:2048
	ds_read_b128 v[156:159], v224 offset:3072
	ds_read_b128 v[160:163], v224 offset:4096
	ds_read_b128 v[164:167], v224 offset:5120
	ds_read_b128 v[168:171], v224 offset:6144
	ds_read_b128 v[172:175], v224 offset:7168
	global_load_lds_dwordx4 v[176:177], off
	v_lshl_add_u64 v[176:177], s[14:15], 0, v[194:195]
	s_add_i32 m0, s5, 0xe000
	s_nop 0
	global_load_lds_dwordx4 v[176:177], off
	s_waitcnt lgkmcnt(8)
	s_barrier
	s_waitcnt lgkmcnt(0)
	s_setprio 1
	s_waitcnt lgkmcnt(0)
	v_mfma_f32_16x16x32_bf16 v[124:127], v[128:131], v[144:147], v[124:127]
	v_mfma_f32_16x16x32_bf16 v[120:123], v[136:139], v[144:147], v[120:123]
	v_mfma_f32_16x16x32_bf16 v[108:111], v[128:131], v[152:155], v[108:111]
	v_mfma_f32_16x16x32_bf16 v[104:107], v[136:139], v[152:155], v[104:107]
	v_mfma_f32_16x16x32_bf16 v[92:95], v[128:131], v[160:163], v[92:95]
	v_mfma_f32_16x16x32_bf16 v[88:91], v[136:139], v[160:163], v[88:91]
	v_mfma_f32_16x16x32_bf16 v[76:79], v[128:131], v[168:171], v[76:79]
	v_mfma_f32_16x16x32_bf16 v[72:75], v[136:139], v[168:171], v[72:75]
	v_mfma_f32_16x16x32_bf16 v[124:127], v[132:135], v[148:151], v[124:127]
	v_mfma_f32_16x16x32_bf16 v[120:123], v[140:143], v[148:151], v[120:123]
	v_mfma_f32_16x16x32_bf16 v[108:111], v[132:135], v[156:159], v[108:111]
	v_mfma_f32_16x16x32_bf16 v[104:107], v[140:143], v[156:159], v[104:107]
	v_mfma_f32_16x16x32_bf16 v[92:95], v[132:135], v[164:167], v[92:95]
	v_mfma_f32_16x16x32_bf16 v[88:91], v[140:143], v[164:167], v[88:91]
	v_mfma_f32_16x16x32_bf16 v[76:79], v[132:135], v[172:175], v[76:79]
	v_mfma_f32_16x16x32_bf16 v[72:75], v[140:143], v[172:175], v[72:75]
	s_setprio 0
	s_barrier
	s_add_i32 s59, s50, s1
	v_lshl_add_u64 v[204:205], s[16:17], 0, v[186:187]
	s_mov_b32 m0, s59
	ds_read_b128 v[176:179], v225
	ds_read_b128 v[180:183], v225 offset:1024
	ds_read_b128 v[196:199], v225 offset:2048
	ds_read_b128 v[200:203], v225 offset:3072
	global_load_lds_dwordx4 v[204:205], off
	v_lshl_add_u64 v[206:207], s[16:17], 0, v[190:191]
	s_add_i32 m0, s59, 0x2000
	s_nop 0
	global_load_lds_dwordx4 v[206:207], off
	s_barrier
	s_waitcnt lgkmcnt(0)
	s_setprio 1
	s_waitcnt lgkmcnt(0)
	v_mfma_f32_16x16x32_bf16 v[116:119], v[176:179], v[144:147], v[116:119]
	v_mfma_f32_16x16x32_bf16 v[112:115], v[196:199], v[144:147], v[112:115]
	v_mfma_f32_16x16x32_bf16 v[100:103], v[176:179], v[152:155], v[100:103]
	v_mfma_f32_16x16x32_bf16 v[96:99], v[196:199], v[152:155], v[96:99]
	v_mfma_f32_16x16x32_bf16 v[84:87], v[176:179], v[160:163], v[84:87]
	v_mfma_f32_16x16x32_bf16 v[80:83], v[196:199], v[160:163], v[80:83]
	v_mfma_f32_16x16x32_bf16 v[68:71], v[176:179], v[168:171], v[68:71]
	v_mfma_f32_16x16x32_bf16 v[64:67], v[196:199], v[168:171], v[64:67]
	v_mfma_f32_16x16x32_bf16 v[116:119], v[180:183], v[148:151], v[116:119]
	v_mfma_f32_16x16x32_bf16 v[112:115], v[200:203], v[148:151], v[112:115]
	v_mfma_f32_16x16x32_bf16 v[100:103], v[180:183], v[156:159], v[100:103]
	v_mfma_f32_16x16x32_bf16 v[96:99], v[200:203], v[156:159], v[96:99]
	v_mfma_f32_16x16x32_bf16 v[84:87], v[180:183], v[164:167], v[84:87]
	v_mfma_f32_16x16x32_bf16 v[80:83], v[200:203], v[164:167], v[80:83]
	v_mfma_f32_16x16x32_bf16 v[68:71], v[180:183], v[172:175], v[68:71]
	v_mfma_f32_16x16x32_bf16 v[64:67], v[200:203], v[172:175], v[64:67]
	s_setprio 0
	s_mov_b32 m0, s5
	v_lshl_add_u64 v[208:209], s[40:41], 0, v[184:185]
	s_barrier
	ds_read_b128 v[144:147], v224 offset:16384
	ds_read_b128 v[148:151], v224 offset:17408
	ds_read_b128 v[152:155], v224 offset:18432
	ds_read_b128 v[156:159], v224 offset:19456
	ds_read_b128 v[160:163], v224 offset:20480
	ds_read_b128 v[164:167], v224 offset:21504
	ds_read_b128 v[168:171], v224 offset:22528
	ds_read_b128 v[172:175], v224 offset:23552
	global_load_lds_dwordx4 v[208:209], off
	v_lshl_add_u64 v[210:211], s[40:41], 0, v[188:189]
	s_mov_b32 m0, s43
	s_nop 0
	global_load_lds_dwordx4 v[210:211], off
	s_barrier
	s_waitcnt lgkmcnt(0)
	s_cbranch_vccnz .Lskp6_2
	s_setprio 1
	s_waitcnt lgkmcnt(0)
	v_mfma_f32_16x16x32_bf16 v[60:63], v[128:131], v[144:147], v[60:63]
	v_mfma_f32_16x16x32_bf16 v[56:59], v[136:139], v[144:147], v[56:59]
	v_mfma_f32_16x16x32_bf16 v[44:47], v[128:131], v[152:155], v[44:47]
	v_mfma_f32_16x16x32_bf16 v[40:43], v[136:139], v[152:155], v[40:43]
	v_mfma_f32_16x16x32_bf16 v[28:31], v[128:131], v[160:163], v[28:31]
	v_mfma_f32_16x16x32_bf16 v[24:27], v[136:139], v[160:163], v[24:27]
	v_mfma_f32_16x16x32_bf16 v[12:15], v[128:131], v[168:171], v[12:15]
	v_mfma_f32_16x16x32_bf16 v[8:11], v[136:139], v[168:171], v[8:11]
	v_mfma_f32_16x16x32_bf16 v[60:63], v[132:135], v[148:151], v[60:63]
	v_mfma_f32_16x16x32_bf16 v[56:59], v[140:143], v[148:151], v[56:59]
	v_mfma_f32_16x16x32_bf16 v[44:47], v[132:135], v[156:159], v[44:47]
	v_mfma_f32_16x16x32_bf16 v[40:43], v[140:143], v[156:159], v[40:43]
	v_mfma_f32_16x16x32_bf16 v[28:31], v[132:135], v[164:167], v[28:31]
	v_mfma_f32_16x16x32_bf16 v[24:27], v[140:143], v[164:167], v[24:27]
	v_mfma_f32_16x16x32_bf16 v[12:15], v[132:135], v[172:175], v[12:15]
	v_mfma_f32_16x16x32_bf16 v[8:11], v[140:143], v[172:175], v[8:11]
	s_setprio 0

; #define PG8_STAGE(bufoff, gbase, voff) do { _Pragma("unroll") for (int _i = 0; _i < 2; ++_i) \
;         __builtin_amdgcn_global_load_lds((const unsigned*)((const char*)(gbase) + (voff)[_i]), (LAS unsigned*)(lds + (bufoff) + ldsw + _i * 8192), 16, 0, 0); } while (0)
; #define PG8_LDA(dst, b, h) do { _Pragma("unroll") for (int m = 0; m < 4; ++m) _Pragma("unroll") for (int k = 0; k < 2; ++k) dst[m][k] = *(const LAS bf16x8*)(lds + PG8_SA(b, h) + aoff + m * 2048 + k * 1024); } while (0)
; #define PG8_LDB(dst, b, h) do { _Pragma("unroll") for (int n = 0; n < 2; ++n) _Pragma("unroll") for (int k = 0; k < 2; ++k) dst[n][k] = *(const LAS bf16x8*)(lds + PG8_SB(b, h) + boff + n * 2048 + k * 1024); } while (0)
; #define PG8_MMA(ai, bj, At, Bt) do { __builtin_amdgcn_s_setprio(1); _Pragma("unroll") for (int m = 0; m < 4; ++m) _Pragma("unroll") for (int n = 0; n < 2; ++n) _Pragma("unroll") for (int k = 0; k < 2; ++k) \
;         acc[ai][bj][m][n] = __builtin_amdgcn_mfma_f32_16x16x32_bf16(Bt[n][k], At[m][k], acc[ai][bj][m][n], 0, 0, 0); __builtin_amdgcn_s_setprio(0); } while (0)
; #define PG8_WAIT_L(n) asm volatile("s_waitcnt lgkmcnt(" #n ")" ::: "memory")
; #define PG8_BAR __builtin_amdgcn_s_barrier()
; #define PG8_SCHED __builtin_amdgcn_sched_barrier(0)
; template <class Epi, class Sched>
; __device__ __forceinline__ void gemm_phase(LAS unsigned char* lds, const int K, const Sched& S, const Epi& E) {
;     ...
;             PG8_LDB(B0, 0, 0); PG8_SCHED; PG8_LDA(At, 0, 0); PG8_STAGE(PG8_SA(1, 1), a1 + hstep, voffA);
;             PG8_WAIT_L(8); PG8_BAR; PG8_WAIT_L(0); PG8_MMA(0, 0, At, B0); PG8_BAR; PG8_SCHED;
;             PG8_LDB(B1, 0, 1); PG8_STAGE(PG8_SB(0, 0), b2, voffB);
;             PG8_BAR; PG8_WAIT_L(0); PG8_MMA(0, 1, At, B1); PG8_BAR;
;             PG8_LDA(At, 0, 1); PG8_STAGE(PG8_SA(0, 0), a2, voffA);
;             PG8_BAR; PG8_WAIT_L(0); PG8_MMA(1, 0, At, B0); PG8_BAR; PG8_SCHED;
;     __device__ __forceinline__ void operator()(Acc& acc, const Unit& u, int wr, int wc, int fr, int fq) const {
;     ...
;             bf16_t* O = (bf16_t*)(ws + R_A); const float* ssq = (const float*)(ws + W_SSQ2);
;             float rsv[2][4];
; #pragma unroll
;             for (int ai = 0; ai < 2; ++ai)
; #pragma unroll
;                 for (int m = 0; m < 4; ++m) rsv[ai][m] = ssq[row0 + ai * 128 + m * 16];
.LBB0_1370:
	s_ashr_i32 s19, s18, 31
	s_lshl_b64 s[20:21], s[18:19], 19
	s_add_u32 s20, s33, s20
	s_addc_u32 s21, s34, s21
	s_and_b64 s[22:23], s[30:31], exec
	s_cselect_b32 s19, s21, s27
	s_cselect_b32 s44, s20, s26
	s_ashr_i32 s17, s16, 31
	s_lshl_b64 s[22:23], s[16:17], 19
	s_add_u32 s22, s3, s22
	s_addc_u32 s23, s4, s23
	s_and_b64 s[30:31], s[30:31], exec
	s_cselect_b32 s17, s23, s29
	s_cselect_b32 s45, s22, s28
	s_add_u32 s26, s26, 0x40080
	s_addc_u32 s27, s27, 0
	s_add_u32 s46, s28, 0x100
	s_addc_u32 s47, s29, 0
	s_mov_b32 s48, -2
	v_lshl_add_u32 v240, s24, 8, v150
	v_ashrrev_i32_e32 v241, 31, v240
	v_lshl_add_u64 v[240:241], v[240:241], 2, s[10:11]
	global_load_dword v232, v[240:241], off
	global_load_dword v233, v[240:241], off offset:64
	global_load_dword v234, v[240:241], off offset:128
	global_load_dword v235, v[240:241], off offset:192
	global_load_dword v236, v[240:241], off offset:512
	global_load_dword v237, v[240:241], off offset:576
	global_load_dword v238, v[240:241], off offset:640
	global_load_dword v239, v[240:241], off offset:704
	s_cmpk_eq_i32 s24, 0x100
	s_cselect_b64 vcc, -1, 0
	ds_read_b128 v[142:145], v152
	ds_read_b128 v[146:149], v152 offset:1024
	ds_read_b128 v[156:159], v152 offset:2048
	ds_read_b128 v[160:163], v152 offset:3072
	s_add_u32 s28, s26, 0xfffc0080
	s_addc_u32 s29, s27, -1
	s_cmp_eq_u32 s48, 12
	s_cselect_b32 s31, s19, s29
	s_cselect_b32 s30, s44, s28
	s_cselect_b32 s29, s17, s47
	s_cselect_b32 s28, s45, s46
	v_lshl_add_u64 v[196:197], s[26:27], 0, v[138:139]
	s_add_i32 m0, s5, 0xc000
	ds_read_b128 v[164:167], v153
	ds_read_b128 v[168:171], v153 offset:1024
	ds_read_b128 v[172:175], v153 offset:2048
	ds_read_b128 v[176:179], v153 offset:3072
	ds_read_b128 v[180:183], v153 offset:4096
	ds_read_b128 v[184:187], v153 offset:5120
	ds_read_b128 v[188:191], v153 offset:6144
	ds_read_b128 v[192:195], v153 offset:7168
	global_load_lds_dwordx4 v[196:197], off
	v_lshl_add_u64 v[196:197], s[26:27], 0, v[140:141]
	s_add_i32 m0, s5, 0xe000
	s_nop 0
	global_load_lds_dwordx4 v[196:197], off
	s_waitcnt lgkmcnt(8)
	s_barrier
	s_waitcnt lgkmcnt(0)
	s_setprio 1
	s_waitcnt lgkmcnt(0)
	v_mfma_f32_16x16x32_bf16 v[124:127], v[142:145], v[164:167], 0
	v_mfma_f32_16x16x32_bf16 v[120:123], v[156:159], v[164:167], 0
	v_mfma_f32_16x16x32_bf16 v[108:111], v[142:145], v[172:175], 0
	v_mfma_f32_16x16x32_bf16 v[100:103], v[156:159], v[172:175], 0
	v_mfma_f32_16x16x32_bf16 v[92:95], v[142:145], v[180:183], 0
	v_mfma_f32_16x16x32_bf16 v[84:87], v[156:159], v[180:183], 0
	v_mfma_f32_16x16x32_bf16 v[76:79], v[142:145], v[188:191], 0
	v_mfma_f32_16x16x32_bf16 v[68:71], v[156:159], v[188:191], 0
	v_mfma_f32_16x16x32_bf16 v[124:127], v[146:149], v[168:171], v[124:127]
	v_mfma_f32_16x16x32_bf16 v[120:123], v[160:163], v[168:171], v[120:123]
	v_mfma_f32_16x16x32_bf16 v[108:111], v[146:149], v[176:179], v[108:111]
	v_mfma_f32_16x16x32_bf16 v[100:103], v[160:163], v[176:179], v[100:103]
	v_mfma_f32_16x16x32_bf16 v[92:95], v[146:149], v[184:187], v[92:95]
	v_mfma_f32_16x16x32_bf16 v[84:87], v[160:163], v[184:187], v[84:87]
	v_mfma_f32_16x16x32_bf16 v[76:79], v[146:149], v[192:195], v[76:79]
	v_mfma_f32_16x16x32_bf16 v[68:71], v[160:163], v[192:195], v[68:71]
	s_setprio 0
	s_barrier
	s_add_i32 s49, s41, s1
	v_lshl_add_u64 v[212:213], s[28:29], 0, v[130:131]
	s_mov_b32 m0, s49
	ds_read_b128 v[196:199], v154
	ds_read_b128 v[200:203], v154 offset:1024
	ds_read_b128 v[204:207], v154 offset:2048
	ds_read_b128 v[208:211], v154 offset:3072
	global_load_lds_dwordx4 v[212:213], off
	v_lshl_add_u64 v[214:215], s[28:29], 0, v[134:135]
	s_add_i32 m0, s49, 0x2000
	s_nop 0
	global_load_lds_dwordx4 v[214:215], off
	s_barrier
	s_waitcnt lgkmcnt(0)
	s_setprio 1
	s_waitcnt lgkmcnt(0)
	v_mfma_f32_16x16x32_bf16 v[116:119], v[196:199], v[164:167], 0
	v_mfma_f32_16x16x32_bf16 v[112:115], v[204:207], v[164:167], 0
	v_mfma_f32_16x16x32_bf16 v[104:107], v[196:199], v[172:175], 0
	v_mfma_f32_16x16x32_bf16 v[96:99], v[204:207], v[172:175], 0
	v_mfma_f32_16x16x32_bf16 v[88:91], v[196:199], v[180:183], 0
	v_mfma_f32_16x16x32_bf16 v[80:83], v[204:207], v[180:183], 0
	v_mfma_f32_16x16x32_bf16 v[72:75], v[196:199], v[188:191], 0
	v_mfma_f32_16x16x32_bf16 v[64:67], v[204:207], v[188:191], 0
	v_mfma_f32_16x16x32_bf16 v[116:119], v[200:203], v[168:171], v[116:119]
	v_mfma_f32_16x16x32_bf16 v[112:115], v[208:211], v[168:171], v[112:115]
	v_mfma_f32_16x16x32_bf16 v[104:107], v[200:203], v[176:179], v[104:107]
	v_mfma_f32_16x16x32_bf16 v[96:99], v[208:211], v[176:179], v[96:99]
	v_mfma_f32_16x16x32_bf16 v[88:91], v[200:203], v[184:187], v[88:91]
	v_mfma_f32_16x16x32_bf16 v[80:83], v[208:211], v[184:187], v[80:83]
	v_mfma_f32_16x16x32_bf16 v[72:75], v[200:203], v[192:195], v[72:75]
	v_mfma_f32_16x16x32_bf16 v[64:67], v[208:211], v[192:195], v[64:67]
	s_setprio 0
	s_mov_b32 m0, s5
	v_lshl_add_u64 v[216:217], s[30:31], 0, v[128:129]
	s_barrier
	ds_read_b128 v[164:167], v153 offset:16384
	ds_read_b128 v[168:171], v153 offset:17408
	ds_read_b128 v[172:175], v153 offset:18432
	ds_read_b128 v[176:179], v153 offset:19456
	ds_read_b128 v[180:183], v153 offset:20480
	ds_read_b128 v[184:187], v153 offset:21504
	ds_read_b128 v[188:191], v153 offset:22528
	ds_read_b128 v[192:195], v153 offset:23552
	global_load_lds_dwordx4 v[216:217], off
	v_lshl_add_u64 v[218:219], s[30:31], 0, v[132:133]
	s_mov_b32 m0, s35
	s_nop 0
	global_load_lds_dwordx4 v[218:219], off
	s_barrier
	s_waitcnt lgkmcnt(0)
	s_cbranch_vccnz .Lskp7_2_p
	s_setprio 1
	s_waitcnt lgkmcnt(0)
	v_mfma_f32_16x16x32_bf16 v[60:63], v[142:145], v[164:167], 0
	v_mfma_f32_16x16x32_bf16 v[56:59], v[156:159], v[164:167], 0
	v_mfma_f32_16x16x32_bf16 v[44:47], v[142:145], v[172:175], 0
	v_mfma_f32_16x16x32_bf16 v[40:43], v[156:159], v[172:175], 0
	v_mfma_f32_16x16x32_bf16 v[28:31], v[142:145], v[180:183], 0
	v_mfma_f32_16x16x32_bf16 v[24:27], v[156:159], v[180:183], 0
	v_mfma_f32_16x16x32_bf16 v[12:15], v[142:145], v[188:191], 0
	v_mfma_f32_16x16x32_bf16 v[8:11], v[156:159], v[188:191], 0
	v_mfma_f32_16x16x32_bf16 v[60:63], v[146:149], v[168:171], v[60:63]
	v_mfma_f32_16x16x32_bf16 v[56:59], v[160:163], v[168:171], v[56:59]
	v_mfma_f32_16x16x32_bf16 v[44:47], v[146:149], v[176:179], v[44:47]
	v_mfma_f32_16x16x32_bf16 v[40:43], v[160:163], v[176:179], v[40:43]
	v_mfma_f32_16x16x32_bf16 v[28:31], v[146:149], v[184:187], v[28:31]
	v_mfma_f32_16x16x32_bf16 v[24:27], v[160:163], v[184:187], v[24:27]
	v_mfma_f32_16x16x32_bf16 v[12:15], v[146:149], v[192:195], v[12:15]
	v_mfma_f32_16x16x32_bf16 v[8:11], v[160:163], v[192:195], v[8:11]
	s_setprio 0
; #define PG8_STAGE(bufoff, gbase, voff) do { _Pragma("unroll") for (int _i = 0; _i < 2; ++_i) \
;         __builtin_amdgcn_global_load_lds((const unsigned*)((const char*)(gbase) + (voff)[_i]), (LAS unsigned*)(lds + (bufoff) + ldsw + _i * 8192), 16, 0, 0); } while (0)
; #define PG8_MMA(ai, bj, At, Bt) do { __builtin_amdgcn_s_setprio(1); _Pragma("unroll") for (int m = 0; m < 4; ++m) _Pragma("unroll") for (int n = 0; n < 2; ++n) _Pragma("unroll") for (int k = 0; k < 2; ++k) \
;         acc[ai][bj][m][n] = __builtin_amdgcn_mfma_f32_16x16x32_bf16(Bt[n][k], At[m][k], acc[ai][bj][m][n], 0, 0, 0); __builtin_amdgcn_s_setprio(0); } while (0)
; #define PG8_WAIT_V(n) asm volatile("s_waitcnt vmcnt(" #n ")" ::: "memory")
; #define PG8_BAR __builtin_amdgcn_s_barrier()
; template <class Epi, class Sched>
; __device__ __forceinline__ void gemm_phase(LAS unsigned char* lds, const int K, const Sched& S, const Epi& E) {
;     ...
;             PG8_STAGE(PG8_SB(0, 1), b2 + hstep, voffB);
;             PG8_WAIT_V(6); PG8_BAR; PG8_MMA(1, 1, At, B1); PG8_BAR;
.Lskp7_2_p:
	s_barrier
	s_add_u32 s50, s28, 0x40000
	s_addc_u32 s51, s29, 0
	s_add_i32 s49, s42, s1
	v_lshl_add_u64 v[142:143], s[50:51], 0, v[130:131]
	s_mov_b32 m0, s49
	s_nop 0
	global_load_lds_dwordx4 v[142:143], off
	v_lshl_add_u64 v[142:143], s[50:51], 0, v[134:135]
	s_add_i32 m0, s49, 0x2000
	s_nop 0
	global_load_lds_dwordx4 v[142:143], off
	s_waitcnt vmcnt(6)
	s_barrier
	s_cbranch_vccnz .Lskp7_3_p
	s_setprio 1
	v_mfma_f32_16x16x32_bf16 v[52:55], v[196:199], v[164:167], 0
	v_mfma_f32_16x16x32_bf16 v[48:51], v[204:207], v[164:167], 0
	v_mfma_f32_16x16x32_bf16 v[36:39], v[196:199], v[172:175], 0
	v_mfma_f32_16x16x32_bf16 v[32:35], v[204:207], v[172:175], 0
	v_mfma_f32_16x16x32_bf16 v[20:23], v[196:199], v[180:183], 0
	v_mfma_f32_16x16x32_bf16 v[16:19], v[204:207], v[180:183], 0
	v_mfma_f32_16x16x32_bf16 v[4:7], v[196:199], v[188:191], 0
	v_mfma_f32_16x16x32_bf16 v[0:3], v[204:207], v[188:191], 0
	v_mfma_f32_16x16x32_bf16 v[52:55], v[200:203], v[168:171], v[52:55]
	v_mfma_f32_16x16x32_bf16 v[48:51], v[208:211], v[168:171], v[48:51]
	v_mfma_f32_16x16x32_bf16 v[36:39], v[200:203], v[176:179], v[36:39]
	v_mfma_f32_16x16x32_bf16 v[32:35], v[208:211], v[176:179], v[32:35]
	v_mfma_f32_16x16x32_bf16 v[20:23], v[200:203], v[184:187], v[20:23]
	v_mfma_f32_16x16x32_bf16 v[16:19], v[208:211], v[184:187], v[16:19]
	v_mfma_f32_16x16x32_bf16 v[4:7], v[200:203], v[192:195], v[4:7]
	v_mfma_f32_16x16x32_bf16 v[0:3], v[208:211], v[192:195], v[0:3]
	s_setprio 0

; #define PG8_STAGE(bufoff, gbase, voff) do { _Pragma("unroll") for (int _i = 0; _i < 2; ++_i) \
;         __builtin_amdgcn_global_load_lds((const unsigned*)((const char*)(gbase) + (voff)[_i]), (LAS unsigned*)(lds + (bufoff) + ldsw + _i * 8192), 16, 0, 0); } while (0)
; #define PG8_LDA(dst, b, h) do { _Pragma("unroll") for (int m = 0; m < 4; ++m) _Pragma("unroll") for (int k = 0; k < 2; ++k) dst[m][k] = *(const LAS bf16x8*)(lds + PG8_SA(b, h) + aoff + m * 2048 + k * 1024); } while (0)
; #define PG8_LDB(dst, b, h) do { _Pragma("unroll") for (int n = 0; n < 2; ++n) _Pragma("unroll") for (int k = 0; k < 2; ++k) dst[n][k] = *(const LAS bf16x8*)(lds + PG8_SB(b, h) + boff + n * 2048 + k * 1024); } while (0)
; #define PG8_MMA(ai, bj, At, Bt) do { __builtin_amdgcn_s_setprio(1); _Pragma("unroll") for (int m = 0; m < 4; ++m) _Pragma("unroll") for (int n = 0; n < 2; ++n) _Pragma("unroll") for (int k = 0; k < 2; ++k) \
;         acc[ai][bj][m][n] = __builtin_amdgcn_mfma_f32_16x16x32_bf16(Bt[n][k], At[m][k], acc[ai][bj][m][n], 0, 0, 0); __builtin_amdgcn_s_setprio(0); } while (0)
; #define PG8_WAIT_L(n) asm volatile("s_waitcnt lgkmcnt(" #n ")" ::: "memory")
; #define PG8_BAR __builtin_amdgcn_s_barrier()
; #define PG8_SCHED __builtin_amdgcn_sched_barrier(0)
; template <class Epi, class Sched>
; __device__ __forceinline__ void gemm_phase(LAS unsigned char* lds, const int K, const Sched& S, const Epi& E) {
;     ...
;         for (int t = 0; t < nt; t += 2) {
;             const bool last = (t == nt - 2);
;             const char* a1 = cA + (size_t)(t + 1) * kstep;
;             const char* a2 = last ? nA : cA + (size_t)(t + 2) * kstep; const char* b2 = last ? nB : cB + (size_t)(t + 2) * kstep;
;             const char* a3 = a2 + kstep; const char* b3 = b2 + kstep;
;             PG8_LDB(B0, 0, 0); PG8_SCHED; PG8_LDA(At, 0, 0); PG8_STAGE(PG8_SA(1, 1), a1 + hstep, voffA);
;             PG8_WAIT_L(8); PG8_BAR; PG8_WAIT_L(0); PG8_MMA(0, 0, At, B0); PG8_BAR; PG8_SCHED;
;             PG8_LDB(B1, 0, 1); PG8_STAGE(PG8_SB(0, 0), b2, voffB);
;             PG8_BAR; PG8_WAIT_L(0); PG8_MMA(0, 1, At, B1); PG8_BAR;
;             PG8_LDA(At, 0, 1); PG8_STAGE(PG8_SA(0, 0), a2, voffA);
;             PG8_BAR; PG8_WAIT_L(0); PG8_MMA(1, 0, At, B0); PG8_BAR; PG8_SCHED;
.Lskp7_7_p:
	s_add_i32 s48, s48, 2
	s_add_u32 s26, s26, 0x100
	s_addc_u32 s27, s27, 0
	s_add_u32 s46, s46, 0x100
	s_addc_u32 s47, s47, 0
	s_cmp_gt_u32 s48, 13
	s_barrier
	s_cbranch_scc0 .LBB0_1371
.LBB0_1371:
	ds_read_b128 v[142:145], v152
	ds_read_b128 v[146:149], v152 offset:1024
	ds_read_b128 v[156:159], v152 offset:2048
	ds_read_b128 v[160:163], v152 offset:3072
	s_add_u32 s28, s26, 0xfffc0080
	s_addc_u32 s29, s27, -1
	s_cmp_eq_u32 s48, 12
	s_cselect_b32 s31, s19, s29
	s_cselect_b32 s30, s44, s28
	s_cselect_b32 s29, s17, s47
	s_cselect_b32 s28, s45, s46
	v_lshl_add_u64 v[196:197], s[26:27], 0, v[138:139]
	s_add_i32 m0, s5, 0xc000
	ds_read_b128 v[164:167], v153
	ds_read_b128 v[168:171], v153 offset:1024
	ds_read_b128 v[172:175], v153 offset:2048
	ds_read_b128 v[176:179], v153 offset:3072
	ds_read_b128 v[180:183], v153 offset:4096
	ds_read_b128 v[184:187], v153 offset:5120
	ds_read_b128 v[188:191], v153 offset:6144
	ds_read_b128 v[192:195], v153 offset:7168
	global_load_lds_dwordx4 v[196:197], off
	v_lshl_add_u64 v[196:197], s[26:27], 0, v[140:141]
	s_add_i32 m0, s5, 0xe000
	s_nop 0
	global_load_lds_dwordx4 v[196:197], off
	s_waitcnt lgkmcnt(8)
	s_barrier
	s_waitcnt lgkmcnt(0)
	s_setprio 1
	s_waitcnt lgkmcnt(0)
	v_mfma_f32_16x16x32_bf16 v[124:127], v[142:145], v[164:167], v[124:127]
	v_mfma_f32_16x16x32_bf16 v[120:123], v[156:159], v[164:167], v[120:123]
	v_mfma_f32_16x16x32_bf16 v[108:111], v[142:145], v[172:175], v[108:111]
	v_mfma_f32_16x16x32_bf16 v[100:103], v[156:159], v[172:175], v[100:103]
	v_mfma_f32_16x16x32_bf16 v[92:95], v[142:145], v[180:183], v[92:95]
	v_mfma_f32_16x16x32_bf16 v[84:87], v[156:159], v[180:183], v[84:87]
	v_mfma_f32_16x16x32_bf16 v[76:79], v[142:145], v[188:191], v[76:79]
	v_mfma_f32_16x16x32_bf16 v[68:71], v[156:159], v[188:191], v[68:71]
	v_mfma_f32_16x16x32_bf16 v[124:127], v[146:149], v[168:171], v[124:127]
	v_mfma_f32_16x16x32_bf16 v[120:123], v[160:163], v[168:171], v[120:123]
	v_mfma_f32_16x16x32_bf16 v[108:111], v[146:149], v[176:179], v[108:111]
	v_mfma_f32_16x16x32_bf16 v[100:103], v[160:163], v[176:179], v[100:103]
	v_mfma_f32_16x16x32_bf16 v[92:95], v[146:149], v[184:187], v[92:95]
	v_mfma_f32_16x16x32_bf16 v[84:87], v[160:163], v[184:187], v[84:87]
	v_mfma_f32_16x16x32_bf16 v[76:79], v[146:149], v[192:195], v[76:79]
	v_mfma_f32_16x16x32_bf16 v[68:71], v[160:163], v[192:195], v[68:71]
	s_setprio 0
	s_barrier
	s_add_i32 s49, s41, s1
	v_lshl_add_u64 v[212:213], s[28:29], 0, v[130:131]
	s_mov_b32 m0, s49
	ds_read_b128 v[196:199], v154
	ds_read_b128 v[200:203], v154 offset:1024
	ds_read_b128 v[204:207], v154 offset:2048
	ds_read_b128 v[208:211], v154 offset:3072
	global_load_lds_dwordx4 v[212:213], off
	v_lshl_add_u64 v[214:215], s[28:29], 0, v[134:135]
	s_add_i32 m0, s49, 0x2000
	s_nop 0
	global_load_lds_dwordx4 v[214:215], off
	s_barrier
	s_waitcnt lgkmcnt(0)
	s_setprio 1
	s_waitcnt lgkmcnt(0)
	v_mfma_f32_16x16x32_bf16 v[116:119], v[196:199], v[164:167], v[116:119]
	v_mfma_f32_16x16x32_bf16 v[112:115], v[204:207], v[164:167], v[112:115]
	v_mfma_f32_16x16x32_bf16 v[104:107], v[196:199], v[172:175], v[104:107]
	v_mfma_f32_16x16x32_bf16 v[96:99], v[204:207], v[172:175], v[96:99]
	v_mfma_f32_16x16x32_bf16 v[88:91], v[196:199], v[180:183], v[88:91]
	v_mfma_f32_16x16x32_bf16 v[80:83], v[204:207], v[180:183], v[80:83]
	v_mfma_f32_16x16x32_bf16 v[72:75], v[196:199], v[188:191], v[72:75]
	v_mfma_f32_16x16x32_bf16 v[64:67], v[204:207], v[188:191], v[64:67]
	v_mfma_f32_16x16x32_bf16 v[116:119], v[200:203], v[168:171], v[116:119]
	v_mfma_f32_16x16x32_bf16 v[112:115], v[208:211], v[168:171], v[112:115]
	v_mfma_f32_16x16x32_bf16 v[104:107], v[200:203], v[176:179], v[104:107]
	v_mfma_f32_16x16x32_bf16 v[96:99], v[208:211], v[176:179], v[96:99]
	v_mfma_f32_16x16x32_bf16 v[88:91], v[200:203], v[184:187], v[88:91]
	v_mfma_f32_16x16x32_bf16 v[80:83], v[208:211], v[184:187], v[80:83]
	v_mfma_f32_16x16x32_bf16 v[72:75], v[200:203], v[192:195], v[72:75]
	v_mfma_f32_16x16x32_bf16 v[64:67], v[208:211], v[192:195], v[64:67]
	s_setprio 0
	s_mov_b32 m0, s5
	v_lshl_add_u64 v[216:217], s[30:31], 0, v[128:129]
	s_barrier
	ds_read_b128 v[164:167], v153 offset:16384
	ds_read_b128 v[168:171], v153 offset:17408
	ds_read_b128 v[172:175], v153 offset:18432
	ds_read_b128 v[176:179], v153 offset:19456
	ds_read_b128 v[180:183], v153 offset:20480
	ds_read_b128 v[184:187], v153 offset:21504
	ds_read_b128 v[188:191], v153 offset:22528
	ds_read_b128 v[192:195], v153 offset:23552
	global_load_lds_dwordx4 v[216:217], off
	v_lshl_add_u64 v[218:219], s[30:31], 0, v[132:133]
	s_mov_b32 m0, s35
	s_nop 0
	global_load_lds_dwordx4 v[218:219], off
	s_barrier
	s_waitcnt lgkmcnt(0)
	s_cbranch_vccnz .Lskp7_2
	s_setprio 1
	s_waitcnt lgkmcnt(0)
	v_mfma_f32_16x16x32_bf16 v[60:63], v[142:145], v[164:167], v[60:63]
	v_mfma_f32_16x16x32_bf16 v[56:59], v[156:159], v[164:167], v[56:59]
	v_mfma_f32_16x16x32_bf16 v[44:47], v[142:145], v[172:175], v[44:47]
	v_mfma_f32_16x16x32_bf16 v[40:43], v[156:159], v[172:175], v[40:43]
	v_mfma_f32_16x16x32_bf16 v[28:31], v[142:145], v[180:183], v[28:31]
	v_mfma_f32_16x16x32_bf16 v[24:27], v[156:159], v[180:183], v[24:27]
	v_mfma_f32_16x16x32_bf16 v[12:15], v[142:145], v[188:191], v[12:15]
	v_mfma_f32_16x16x32_bf16 v[8:11], v[156:159], v[188:191], v[8:11]
	v_mfma_f32_16x16x32_bf16 v[60:63], v[146:149], v[168:171], v[60:63]
	v_mfma_f32_16x16x32_bf16 v[56:59], v[160:163], v[168:171], v[56:59]
	v_mfma_f32_16x16x32_bf16 v[44:47], v[146:149], v[176:179], v[44:47]
	v_mfma_f32_16x16x32_bf16 v[40:43], v[160:163], v[176:179], v[40:43]
	v_mfma_f32_16x16x32_bf16 v[28:31], v[146:149], v[184:187], v[28:31]
	v_mfma_f32_16x16x32_bf16 v[24:27], v[160:163], v[184:187], v[24:27]
	v_mfma_f32_16x16x32_bf16 v[12:15], v[146:149], v[192:195], v[12:15]
	v_mfma_f32_16x16x32_bf16 v[8:11], v[160:163], v[192:195], v[8:11]
	s_setprio 0

; #define PG8_STAGE(bufoff, gbase, voff) do { _Pragma("unroll") for (int _i = 0; _i < 2; ++_i) \
;         __builtin_amdgcn_global_load_lds((const unsigned*)((const char*)(gbase) + (voff)[_i]), (LAS unsigned*)(lds + (bufoff) + ldsw + _i * 8192), 16, 0, 0); } while (0)
; #define PG8_LDA(dst, b, h) do { _Pragma("unroll") for (int m = 0; m < 4; ++m) _Pragma("unroll") for (int k = 0; k < 2; ++k) dst[m][k] = *(const LAS bf16x8*)(lds + PG8_SA(b, h) + aoff + m * 2048 + k * 1024); } while (0)
; #define PG8_LDB(dst, b, h) do { _Pragma("unroll") for (int n = 0; n < 2; ++n) _Pragma("unroll") for (int k = 0; k < 2; ++k) dst[n][k] = *(const LAS bf16x8*)(lds + PG8_SB(b, h) + boff + n * 2048 + k * 1024); } while (0)
; #define PG8_MMA(ai, bj, At, Bt) do { __builtin_amdgcn_s_setprio(1); _Pragma("unroll") for (int m = 0; m < 4; ++m) _Pragma("unroll") for (int n = 0; n < 2; ++n) _Pragma("unroll") for (int k = 0; k < 2; ++k) \
;         acc[ai][bj][m][n] = __builtin_amdgcn_mfma_f32_16x16x32_bf16(Bt[n][k], At[m][k], acc[ai][bj][m][n], 0, 0, 0); __builtin_amdgcn_s_setprio(0); } while (0)
; #define PG8_WAIT_L(n) asm volatile("s_waitcnt lgkmcnt(" #n ")" ::: "memory")
; #define PG8_BAR __builtin_amdgcn_s_barrier()
; #define PG8_SCHED __builtin_amdgcn_sched_barrier(0)
; template <class Epi, class Sched>
; __device__ __forceinline__ void gemm_phase(LAS unsigned char* lds, const int K, const Sched& S, const Epi& E) {
;     ...
;             PG8_LDB(B0, 0, 0); PG8_SCHED; PG8_LDA(At, 0, 0); PG8_STAGE(PG8_SA(1, 1), a1 + hstep, voffA);
;             PG8_WAIT_L(8); PG8_BAR; PG8_WAIT_L(0); PG8_MMA(0, 0, At, B0); PG8_BAR; PG8_SCHED;
;             PG8_LDB(B1, 0, 1); PG8_STAGE(PG8_SB(0, 0), b2, voffB);
;             PG8_BAR; PG8_WAIT_L(0); PG8_MMA(0, 1, At, B1); PG8_BAR;
;             PG8_LDA(At, 0, 1); PG8_STAGE(PG8_SA(0, 0), a2, voffA);
;             PG8_BAR; PG8_WAIT_L(0); PG8_MMA(1, 0, At, B0); PG8_BAR; PG8_SCHED;
.LBB0_1446:
	s_add_u32 s48, s14, 0x100
	s_addc_u32 s49, s15, 0
	s_mov_b32 s50, -2
	s_waitcnt vmcnt(16)
	s_cmpk_eq_i32 s47, 0x100
	s_cselect_b64 vcc, -1, 0
	ds_read_b128 v[128:131], v183
	ds_read_b128 v[132:135], v183 offset:1024
	ds_read_b128 v[136:139], v183 offset:2048
	ds_read_b128 v[140:143], v183 offset:3072
	s_add_u32 s14, s12, 0x100
	s_addc_u32 s15, s13, 0
	s_cmp_eq_u32 s50, 40
	s_cselect_b32 s19, s11, s15
	s_cselect_b32 s18, s10, s14
	s_cselect_b32 s17, s1, s49
	s_cselect_b32 s16, s0, s48
	v_lshl_add_u64 v[200:201], s[12:13], 0, v[166:167]
	s_add_i32 m0, s23, 0xc000
	ds_read_b128 v[144:147], v184
	ds_read_b128 v[148:151], v184 offset:1024
	ds_read_b128 v[170:173], v184 offset:2048
	ds_read_b128 v[174:177], v184 offset:3072
	ds_read_b128 v[178:181], v184 offset:4096
	ds_read_b128 v[188:191], v184 offset:5120
	ds_read_b128 v[192:195], v184 offset:6144
	ds_read_b128 v[196:199], v184 offset:7168
	global_load_lds_dwordx4 v[200:201], off
	v_lshl_add_u64 v[200:201], s[12:13], 0, v[168:169]
	s_add_i32 m0, s23, 0xe000
	s_nop 0
	global_load_lds_dwordx4 v[200:201], off
	s_waitcnt lgkmcnt(8)
	s_barrier
	s_waitcnt lgkmcnt(0)
	s_setprio 1
	s_waitcnt lgkmcnt(0)
	v_mfma_f32_16x16x32_bf16 v[124:127], v[128:131], v[144:147], 0
	v_mfma_f32_16x16x32_bf16 v[120:123], v[136:139], v[144:147], 0
	v_mfma_f32_16x16x32_bf16 v[108:111], v[128:131], v[170:173], 0
	v_mfma_f32_16x16x32_bf16 v[104:107], v[136:139], v[170:173], 0
	v_mfma_f32_16x16x32_bf16 v[92:95], v[128:131], v[178:181], 0
	v_mfma_f32_16x16x32_bf16 v[88:91], v[136:139], v[178:181], 0
	v_mfma_f32_16x16x32_bf16 v[76:79], v[128:131], v[192:195], 0
	v_mfma_f32_16x16x32_bf16 v[72:75], v[136:139], v[192:195], 0
	v_mfma_f32_16x16x32_bf16 v[124:127], v[132:135], v[148:151], v[124:127]
	v_mfma_f32_16x16x32_bf16 v[120:123], v[140:143], v[148:151], v[120:123]
	v_mfma_f32_16x16x32_bf16 v[108:111], v[132:135], v[174:177], v[108:111]
	v_mfma_f32_16x16x32_bf16 v[104:107], v[140:143], v[174:177], v[104:107]
	v_mfma_f32_16x16x32_bf16 v[92:95], v[132:135], v[188:191], v[92:95]
	v_mfma_f32_16x16x32_bf16 v[88:91], v[140:143], v[188:191], v[88:91]
	v_mfma_f32_16x16x32_bf16 v[76:79], v[132:135], v[196:199], v[76:79]
	v_mfma_f32_16x16x32_bf16 v[72:75], v[140:143], v[196:199], v[72:75]
	s_setprio 0
	s_barrier
	s_add_i32 s12, s34, s20
	v_lshl_add_u64 v[216:217], s[16:17], 0, v[154:155]
	s_mov_b32 m0, s12
	ds_read_b128 v[200:203], v185
	ds_read_b128 v[204:207], v185 offset:1024
	ds_read_b128 v[208:211], v185 offset:2048
	ds_read_b128 v[212:215], v185 offset:3072
	global_load_lds_dwordx4 v[216:217], off
	v_lshl_add_u64 v[218:219], s[16:17], 0, v[158:159]
	s_add_i32 m0, s12, 0x2000
	s_nop 0
	global_load_lds_dwordx4 v[218:219], off
	s_barrier
	s_waitcnt lgkmcnt(0)
	s_setprio 1
	s_waitcnt lgkmcnt(0)
	v_mfma_f32_16x16x32_bf16 v[116:119], v[200:203], v[144:147], 0
	v_mfma_f32_16x16x32_bf16 v[112:115], v[208:211], v[144:147], 0
	v_mfma_f32_16x16x32_bf16 v[100:103], v[200:203], v[170:173], 0
	v_mfma_f32_16x16x32_bf16 v[96:99], v[208:211], v[170:173], 0
	v_mfma_f32_16x16x32_bf16 v[84:87], v[200:203], v[178:181], 0
	v_mfma_f32_16x16x32_bf16 v[80:83], v[208:211], v[178:181], 0
	v_mfma_f32_16x16x32_bf16 v[68:71], v[200:203], v[192:195], 0
	v_mfma_f32_16x16x32_bf16 v[64:67], v[208:211], v[192:195], 0
	v_mfma_f32_16x16x32_bf16 v[116:119], v[204:207], v[148:151], v[116:119]
	v_mfma_f32_16x16x32_bf16 v[112:115], v[212:215], v[148:151], v[112:115]
	v_mfma_f32_16x16x32_bf16 v[100:103], v[204:207], v[174:177], v[100:103]
	v_mfma_f32_16x16x32_bf16 v[96:99], v[212:215], v[174:177], v[96:99]
	v_mfma_f32_16x16x32_bf16 v[84:87], v[204:207], v[188:191], v[84:87]
	v_mfma_f32_16x16x32_bf16 v[80:83], v[212:215], v[188:191], v[80:83]
	v_mfma_f32_16x16x32_bf16 v[68:71], v[204:207], v[196:199], v[68:71]
	v_mfma_f32_16x16x32_bf16 v[64:67], v[212:215], v[196:199], v[64:67]
	s_setprio 0
	s_mov_b32 m0, s23
	v_lshl_add_u64 v[220:221], s[18:19], 0, v[152:153]
	s_barrier
	ds_read_b128 v[144:147], v184 offset:16384
	ds_read_b128 v[148:151], v184 offset:17408
	ds_read_b128 v[170:173], v184 offset:18432
	ds_read_b128 v[174:177], v184 offset:19456
	ds_read_b128 v[178:181], v184 offset:20480
	ds_read_b128 v[188:191], v184 offset:21504
	ds_read_b128 v[192:195], v184 offset:22528
	ds_read_b128 v[196:199], v184 offset:23552
	global_load_lds_dwordx4 v[220:221], off
	v_lshl_add_u64 v[222:223], s[18:19], 0, v[156:157]
	s_mov_b32 m0, s26
	s_nop 0
	global_load_lds_dwordx4 v[222:223], off
	s_barrier
	s_waitcnt lgkmcnt(0)
	s_cbranch_vccnz .Lskp8_2_p
	s_setprio 1
	s_waitcnt lgkmcnt(0)
	v_mfma_f32_16x16x32_bf16 v[60:63], v[128:131], v[144:147], 0
	v_mfma_f32_16x16x32_bf16 v[56:59], v[136:139], v[144:147], 0
	v_mfma_f32_16x16x32_bf16 v[44:47], v[128:131], v[170:173], 0
	v_mfma_f32_16x16x32_bf16 v[40:43], v[136:139], v[170:173], 0
	v_mfma_f32_16x16x32_bf16 v[28:31], v[128:131], v[178:181], 0
	v_mfma_f32_16x16x32_bf16 v[24:27], v[136:139], v[178:181], 0
	v_mfma_f32_16x16x32_bf16 v[12:15], v[128:131], v[192:195], 0
	v_mfma_f32_16x16x32_bf16 v[8:11], v[136:139], v[192:195], 0
	v_mfma_f32_16x16x32_bf16 v[60:63], v[132:135], v[148:151], v[60:63]
	v_mfma_f32_16x16x32_bf16 v[56:59], v[140:143], v[148:151], v[56:59]
	v_mfma_f32_16x16x32_bf16 v[44:47], v[132:135], v[174:177], v[44:47]
	v_mfma_f32_16x16x32_bf16 v[40:43], v[140:143], v[174:177], v[40:43]
	v_mfma_f32_16x16x32_bf16 v[28:31], v[132:135], v[188:191], v[28:31]
	v_mfma_f32_16x16x32_bf16 v[24:27], v[140:143], v[188:191], v[24:27]
	v_mfma_f32_16x16x32_bf16 v[12:15], v[132:135], v[196:199], v[12:15]
	v_mfma_f32_16x16x32_bf16 v[8:11], v[140:143], v[196:199], v[8:11]
	s_setprio 0
; #define PG8_STAGE(bufoff, gbase, voff) do { _Pragma("unroll") for (int _i = 0; _i < 2; ++_i) \
;         __builtin_amdgcn_global_load_lds((const unsigned*)((const char*)(gbase) + (voff)[_i]), (LAS unsigned*)(lds + (bufoff) + ldsw + _i * 8192), 16, 0, 0); } while (0)
; #define PG8_MMA(ai, bj, At, Bt) do { __builtin_amdgcn_s_setprio(1); _Pragma("unroll") for (int m = 0; m < 4; ++m) _Pragma("unroll") for (int n = 0; n < 2; ++n) _Pragma("unroll") for (int k = 0; k < 2; ++k) \
;         acc[ai][bj][m][n] = __builtin_amdgcn_mfma_f32_16x16x32_bf16(Bt[n][k], At[m][k], acc[ai][bj][m][n], 0, 0, 0); __builtin_amdgcn_s_setprio(0); } while (0)
; #define PG8_WAIT_V(n) asm volatile("s_waitcnt vmcnt(" #n ")" ::: "memory")
; #define PG8_BAR __builtin_amdgcn_s_barrier()
; template <class Epi, class Sched>
; __device__ __forceinline__ void gemm_phase(LAS unsigned char* lds, const int K, const Sched& S, const Epi& E) {
;     ...
;             PG8_STAGE(PG8_SB(0, 1), b2 + hstep, voffB);
;             PG8_WAIT_V(6); PG8_BAR; PG8_MMA(1, 1, At, B1); PG8_BAR;
.Lskp8_2_p:
	s_barrier
	s_add_u32 s12, s16, 0xb0000
	s_addc_u32 s13, s17, 0
	s_add_i32 s51, s35, s20
	v_lshl_add_u64 v[128:129], s[12:13], 0, v[154:155]
	s_mov_b32 m0, s51
	s_nop 0
	global_load_lds_dwordx4 v[128:129], off
	v_lshl_add_u64 v[128:129], s[12:13], 0, v[158:159]
	s_add_i32 m0, s51, 0x2000
	s_nop 0
	global_load_lds_dwordx4 v[128:129], off
	s_waitcnt vmcnt(6)
	s_barrier
	s_cbranch_vccnz .Lskp8_3_p
	s_setprio 1
	v_mfma_f32_16x16x32_bf16 v[52:55], v[200:203], v[144:147], 0
	v_mfma_f32_16x16x32_bf16 v[48:51], v[208:211], v[144:147], 0
	v_mfma_f32_16x16x32_bf16 v[36:39], v[200:203], v[170:173], 0
	v_mfma_f32_16x16x32_bf16 v[32:35], v[208:211], v[170:173], 0
	v_mfma_f32_16x16x32_bf16 v[20:23], v[200:203], v[178:181], 0
	v_mfma_f32_16x16x32_bf16 v[16:19], v[208:211], v[178:181], 0
	v_mfma_f32_16x16x32_bf16 v[4:7], v[200:203], v[192:195], 0
	v_mfma_f32_16x16x32_bf16 v[0:3], v[208:211], v[192:195], 0
	v_mfma_f32_16x16x32_bf16 v[52:55], v[204:207], v[148:151], v[52:55]
	v_mfma_f32_16x16x32_bf16 v[48:51], v[212:215], v[148:151], v[48:51]
	v_mfma_f32_16x16x32_bf16 v[36:39], v[204:207], v[174:177], v[36:39]
	v_mfma_f32_16x16x32_bf16 v[32:35], v[212:215], v[174:177], v[32:35]
	v_mfma_f32_16x16x32_bf16 v[20:23], v[204:207], v[188:191], v[20:23]
	v_mfma_f32_16x16x32_bf16 v[16:19], v[212:215], v[188:191], v[16:19]
	v_mfma_f32_16x16x32_bf16 v[4:7], v[204:207], v[196:199], v[4:7]
	v_mfma_f32_16x16x32_bf16 v[0:3], v[212:215], v[196:199], v[0:3]
	s_setprio 0

; #define PG8_STAGE(bufoff, gbase, voff) do { _Pragma("unroll") for (int _i = 0; _i < 2; ++_i) \
;         __builtin_amdgcn_global_load_lds((const unsigned*)((const char*)(gbase) + (voff)[_i]), (LAS unsigned*)(lds + (bufoff) + ldsw + _i * 8192), 16, 0, 0); } while (0)
; #define PG8_LDA(dst, b, h) do { _Pragma("unroll") for (int m = 0; m < 4; ++m) _Pragma("unroll") for (int k = 0; k < 2; ++k) dst[m][k] = *(const LAS bf16x8*)(lds + PG8_SA(b, h) + aoff + m * 2048 + k * 1024); } while (0)
; #define PG8_LDB(dst, b, h) do { _Pragma("unroll") for (int n = 0; n < 2; ++n) _Pragma("unroll") for (int k = 0; k < 2; ++k) dst[n][k] = *(const LAS bf16x8*)(lds + PG8_SB(b, h) + boff + n * 2048 + k * 1024); } while (0)
; #define PG8_MMA(ai, bj, At, Bt) do { __builtin_amdgcn_s_setprio(1); _Pragma("unroll") for (int m = 0; m < 4; ++m) _Pragma("unroll") for (int n = 0; n < 2; ++n) _Pragma("unroll") for (int k = 0; k < 2; ++k) \
;         acc[ai][bj][m][n] = __builtin_amdgcn_mfma_f32_16x16x32_bf16(Bt[n][k], At[m][k], acc[ai][bj][m][n], 0, 0, 0); __builtin_amdgcn_s_setprio(0); } while (0)
; #define PG8_WAIT_L(n) asm volatile("s_waitcnt lgkmcnt(" #n ")" ::: "memory")
; #define PG8_BAR __builtin_amdgcn_s_barrier()
; #define PG8_SCHED __builtin_amdgcn_sched_barrier(0)
; template <class Epi, class Sched>
; __device__ __forceinline__ void gemm_phase(LAS unsigned char* lds, const int K, const Sched& S, const Epi& E) {
;     ...
;         for (int t = 0; t < nt; t += 2) {
;             const bool last = (t == nt - 2);
;             const char* a1 = cA + (size_t)(t + 1) * kstep;
;             const char* a2 = last ? nA : cA + (size_t)(t + 2) * kstep; const char* b2 = last ? nB : cB + (size_t)(t + 2) * kstep;
;             const char* a3 = a2 + kstep; const char* b3 = b2 + kstep;
;             PG8_LDB(B0, 0, 0); PG8_SCHED; PG8_LDA(At, 0, 0); PG8_STAGE(PG8_SA(1, 1), a1 + hstep, voffA);
;             PG8_WAIT_L(8); PG8_BAR; PG8_WAIT_L(0); PG8_MMA(0, 0, At, B0); PG8_BAR; PG8_SCHED;
;             PG8_LDB(B1, 0, 1); PG8_STAGE(PG8_SB(0, 0), b2, voffB);
;             PG8_BAR; PG8_WAIT_L(0); PG8_MMA(0, 1, At, B1); PG8_BAR;
;             PG8_LDA(At, 0, 1); PG8_STAGE(PG8_SA(0, 0), a2, voffA);
;             PG8_BAR; PG8_WAIT_L(0); PG8_MMA(1, 0, At, B0); PG8_BAR; PG8_SCHED;
.Lskp8_7_p:
	s_add_i32 s50, s50, 2
	s_add_u32 s48, s48, 0x100
	s_addc_u32 s49, s49, 0
	s_cmp_gt_u32 s50, 41
	s_mov_b64 s[12:13], s[14:15]
	s_barrier
	s_cbranch_scc0 .LBB0_1447
.LBB0_1447:
	ds_read_b128 v[128:131], v183
	ds_read_b128 v[132:135], v183 offset:1024
	ds_read_b128 v[136:139], v183 offset:2048
	ds_read_b128 v[140:143], v183 offset:3072
	s_add_u32 s14, s12, 0x100
	s_addc_u32 s15, s13, 0
	s_cmp_eq_u32 s50, 40
	s_cselect_b32 s19, s11, s15
	s_cselect_b32 s18, s10, s14
	s_cselect_b32 s17, s1, s49
	s_cselect_b32 s16, s0, s48
	v_lshl_add_u64 v[200:201], s[12:13], 0, v[166:167]
	s_add_i32 m0, s23, 0xc000
	ds_read_b128 v[144:147], v184
	ds_read_b128 v[148:151], v184 offset:1024
	ds_read_b128 v[170:173], v184 offset:2048
	ds_read_b128 v[174:177], v184 offset:3072
	ds_read_b128 v[178:181], v184 offset:4096
	ds_read_b128 v[188:191], v184 offset:5120
	ds_read_b128 v[192:195], v184 offset:6144
	ds_read_b128 v[196:199], v184 offset:7168
	global_load_lds_dwordx4 v[200:201], off
	v_lshl_add_u64 v[200:201], s[12:13], 0, v[168:169]
	s_add_i32 m0, s23, 0xe000
	s_nop 0
	global_load_lds_dwordx4 v[200:201], off
	s_waitcnt lgkmcnt(8)
	s_barrier
	s_waitcnt lgkmcnt(0)
	s_setprio 1
	s_waitcnt lgkmcnt(0)
	v_mfma_f32_16x16x32_bf16 v[124:127], v[128:131], v[144:147], v[124:127]
	v_mfma_f32_16x16x32_bf16 v[120:123], v[136:139], v[144:147], v[120:123]
	v_mfma_f32_16x16x32_bf16 v[108:111], v[128:131], v[170:173], v[108:111]
	v_mfma_f32_16x16x32_bf16 v[104:107], v[136:139], v[170:173], v[104:107]
	v_mfma_f32_16x16x32_bf16 v[92:95], v[128:131], v[178:181], v[92:95]
	v_mfma_f32_16x16x32_bf16 v[88:91], v[136:139], v[178:181], v[88:91]
	v_mfma_f32_16x16x32_bf16 v[76:79], v[128:131], v[192:195], v[76:79]
	v_mfma_f32_16x16x32_bf16 v[72:75], v[136:139], v[192:195], v[72:75]
	v_mfma_f32_16x16x32_bf16 v[124:127], v[132:135], v[148:151], v[124:127]
	v_mfma_f32_16x16x32_bf16 v[120:123], v[140:143], v[148:151], v[120:123]
	v_mfma_f32_16x16x32_bf16 v[108:111], v[132:135], v[174:177], v[108:111]
	v_mfma_f32_16x16x32_bf16 v[104:107], v[140:143], v[174:177], v[104:107]
	v_mfma_f32_16x16x32_bf16 v[92:95], v[132:135], v[188:191], v[92:95]
	v_mfma_f32_16x16x32_bf16 v[88:91], v[140:143], v[188:191], v[88:91]
	v_mfma_f32_16x16x32_bf16 v[76:79], v[132:135], v[196:199], v[76:79]
	v_mfma_f32_16x16x32_bf16 v[72:75], v[140:143], v[196:199], v[72:75]
	s_setprio 0
	s_barrier
	s_add_i32 s12, s34, s20
	v_lshl_add_u64 v[216:217], s[16:17], 0, v[154:155]
	s_mov_b32 m0, s12
	ds_read_b128 v[200:203], v185
	ds_read_b128 v[204:207], v185 offset:1024
	ds_read_b128 v[208:211], v185 offset:2048
	ds_read_b128 v[212:215], v185 offset:3072
	global_load_lds_dwordx4 v[216:217], off
	v_lshl_add_u64 v[218:219], s[16:17], 0, v[158:159]
	s_add_i32 m0, s12, 0x2000
	s_nop 0
	global_load_lds_dwordx4 v[218:219], off
	s_barrier
	s_waitcnt lgkmcnt(0)
	s_setprio 1
	s_waitcnt lgkmcnt(0)
	v_mfma_f32_16x16x32_bf16 v[116:119], v[200:203], v[144:147], v[116:119]
	v_mfma_f32_16x16x32_bf16 v[112:115], v[208:211], v[144:147], v[112:115]
	v_mfma_f32_16x16x32_bf16 v[100:103], v[200:203], v[170:173], v[100:103]
	v_mfma_f32_16x16x32_bf16 v[96:99], v[208:211], v[170:173], v[96:99]
	v_mfma_f32_16x16x32_bf16 v[84:87], v[200:203], v[178:181], v[84:87]
	v_mfma_f32_16x16x32_bf16 v[80:83], v[208:211], v[178:181], v[80:83]
	v_mfma_f32_16x16x32_bf16 v[68:71], v[200:203], v[192:195], v[68:71]
	v_mfma_f32_16x16x32_bf16 v[64:67], v[208:211], v[192:195], v[64:67]
	v_mfma_f32_16x16x32_bf16 v[116:119], v[204:207], v[148:151], v[116:119]
	v_mfma_f32_16x16x32_bf16 v[112:115], v[212:215], v[148:151], v[112:115]
	v_mfma_f32_16x16x32_bf16 v[100:103], v[204:207], v[174:177], v[100:103]
	v_mfma_f32_16x16x32_bf16 v[96:99], v[212:215], v[174:177], v[96:99]
	v_mfma_f32_16x16x32_bf16 v[84:87], v[204:207], v[188:191], v[84:87]
	v_mfma_f32_16x16x32_bf16 v[80:83], v[212:215], v[188:191], v[80:83]
	v_mfma_f32_16x16x32_bf16 v[68:71], v[204:207], v[196:199], v[68:71]
	v_mfma_f32_16x16x32_bf16 v[64:67], v[212:215], v[196:199], v[64:67]
	s_setprio 0
	s_mov_b32 m0, s23
	v_lshl_add_u64 v[220:221], s[18:19], 0, v[152:153]
	s_barrier
	ds_read_b128 v[144:147], v184 offset:16384
	ds_read_b128 v[148:151], v184 offset:17408
	ds_read_b128 v[170:173], v184 offset:18432
	ds_read_b128 v[174:177], v184 offset:19456
	ds_read_b128 v[178:181], v184 offset:20480
	ds_read_b128 v[188:191], v184 offset:21504
	ds_read_b128 v[192:195], v184 offset:22528
	ds_read_b128 v[196:199], v184 offset:23552
	global_load_lds_dwordx4 v[220:221], off
	v_lshl_add_u64 v[222:223], s[18:19], 0, v[156:157]
	s_mov_b32 m0, s26
	s_nop 0
	global_load_lds_dwordx4 v[222:223], off
	s_barrier
	s_waitcnt lgkmcnt(0)
	s_cbranch_vccnz .Lskp8_2
	s_setprio 1
	s_waitcnt lgkmcnt(0)
	v_mfma_f32_16x16x32_bf16 v[60:63], v[128:131], v[144:147], v[60:63]
	v_mfma_f32_16x16x32_bf16 v[56:59], v[136:139], v[144:147], v[56:59]
	v_mfma_f32_16x16x32_bf16 v[44:47], v[128:131], v[170:173], v[44:47]
	v_mfma_f32_16x16x32_bf16 v[40:43], v[136:139], v[170:173], v[40:43]
	v_mfma_f32_16x16x32_bf16 v[28:31], v[128:131], v[178:181], v[28:31]
	v_mfma_f32_16x16x32_bf16 v[24:27], v[136:139], v[178:181], v[24:27]
	v_mfma_f32_16x16x32_bf16 v[12:15], v[128:131], v[192:195], v[12:15]
	v_mfma_f32_16x16x32_bf16 v[8:11], v[136:139], v[192:195], v[8:11]
	v_mfma_f32_16x16x32_bf16 v[60:63], v[132:135], v[148:151], v[60:63]
	v_mfma_f32_16x16x32_bf16 v[56:59], v[140:143], v[148:151], v[56:59]
	v_mfma_f32_16x16x32_bf16 v[44:47], v[132:135], v[174:177], v[44:47]
	v_mfma_f32_16x16x32_bf16 v[40:43], v[140:143], v[174:177], v[40:43]
	v_mfma_f32_16x16x32_bf16 v[28:31], v[132:135], v[188:191], v[28:31]
	v_mfma_f32_16x16x32_bf16 v[24:27], v[140:143], v[188:191], v[24:27]
	v_mfma_f32_16x16x32_bf16 v[12:15], v[132:135], v[196:199], v[12:15]
	v_mfma_f32_16x16x32_bf16 v[8:11], v[140:143], v[196:199], v[8:11]
	s_setprio 0
